# Resid epilogues: row sum-of-squares cross-lane reduction via v_permlane16_swap/v_permlane32_swap instead of two dependent ds_bpermute round trips per row group (same add order, bit-identical)
# speedup vs baseline: 1.0084x; 1.0014x over previous
; __device__ __forceinline__ unsigned cvt_pk_bf16(float lo, float hi) { unsigned r; asm volatile("v_cvt_pk_bf16_f32 %0, %1, %2" : "=v"(r) : "v"(lo), "v"(hi)); return r; }
;     __device__ __forceinline__ void operator()(const f32x4 (&acc)[2][2][4][2], const Unit& u, int wr, int wc, int fr, int fq, const float (&)[8]) const {
;         const int row0 = u.pm * BM + wr * 64 + fr, col0 = u.pn * BM + wc * 32 + 8 * fq;
;         u32x4 xc[2], xn[2];
;         { const size_t off = (size_t)row0 * 2048 + col0;
; #pragma unroll
;           for (int bj = 0; bj < 2; ++bj) xc[bj] = *(const u32x4*)(xb + off + bj * HALF); }
; #pragma unroll
;         for (int g = 0; g < 8; ++g) { const int ai = g >> 2, m = g & 3, row = row0 + ai * HALF + m * 16; const size_t off = (size_t)row * 2048 + col0; float ss = 0.f;
;             if (g + 1 < 8) { const size_t offn = (size_t)(row0 + ((g + 1) >> 2) * HALF + ((g + 1) & 3) * 16) * 2048 + col0;
; #pragma unroll
;                 for (int bj = 0; bj < 2; ++bj) xn[bj] = *(const u32x4*)(xb + offn + bj * HALF); }
; #pragma unroll
;             for (int bj = 0; bj < 2; ++bj) { const size_t o = off + bj * HALF; const u32x4 xw = xc[bj];
;                 const f32x4 x0 = (f32x4){__uint_as_float(xw.x << 16), __uint_as_float(xw.x & 0xffff0000u), __uint_as_float(xw.y << 16), __uint_as_float(xw.y & 0xffff0000u)};
;                 const f32x4 x1 = (f32x4){__uint_as_float(xw.z << 16), __uint_as_float(xw.z & 0xffff0000u), __uint_as_float(xw.w << 16), __uint_as_float(xw.w & 0xffff0000u)};
;                 const f32x4 v0 = x0 + acc[ai][bj][m][0] * alpha, v1 = x1 + acc[ai][bj][m][1] * alpha;
;                 if (xf) { *(f32x4*)(xf + o) = v0; *(f32x4*)(xf + o + 4) = v1; }
;                 else { u32x4 w; w.x = cvt_pk_bf16(v0[0], v0[1]); w.y = cvt_pk_bf16(v0[2], v0[3]); w.z = cvt_pk_bf16(v1[0], v1[1]); w.w = cvt_pk_bf16(v1[2], v1[3]); *(u32x4*)(xb + o) = w; }
;                 ss += ((v0[0] * v0[0] + v0[1] * v0[1]) + (v0[2] * v0[2] + v0[3] * v0[3])) + ((v1[0] * v1[0] + v1[1] * v1[1]) + (v1[2] * v1[2] + v1[3] * v1[3])); }
;             ss += __shfl_xor(ss, 16); ss += __shfl_xor(ss, 32);
;             if (fq == 0) (void)__hip_atomic_fetch_add((unsigned*)(ssq_out + row), (unsigned)(ss * SSQ_SCALE + 0.5f), __ATOMIC_RELAXED, __HIP_MEMORY_SCOPE_AGENT);
.LBB0_170:
	v_lshl_add_u32 v160, s45, 8, v184
	v_lshl_or_b32 v158, s50, 8, v186
	v_ashrrev_i32_e32 v161, 31, v160
	v_ashrrev_i32_e32 v159, 31, v158
	v_lshlrev_b64 v[132:133], 12, v[160:161]
	v_lshl_add_u64 v[132:133], s[46:47], 0, v[132:133]
	v_lshlrev_b64 v[134:135], 1, v[158:159]
	v_lshl_add_u64 v[166:167], v[132:133], 0, v[134:135]
	global_load_dwordx4 v[188:191], v[166:167], off
	global_load_dwordx4 v[192:195], v[166:167], off offset:256
	v_or_b32_e32 v162, 16, v160
	v_ashrrev_i32_e32 v163, 31, v162
	v_lshlrev_b64 v[132:133], 12, v[162:163]
	v_lshl_add_u64 v[132:133], s[46:47], 0, v[132:133]
	v_lshl_add_u64 v[164:165], v[132:133], 0, v[134:135]
	global_load_dwordx4 v[136:139], v[164:165], off
	global_load_dwordx4 v[132:135], v[164:165], off offset:256
	s_mov_b64 s[14:15], 0x20000
	v_lshl_add_u64 v[248:249], v[166:167], 0, s[14:15]
	global_load_dwordx4 v[200:203], v[248:249], off
	global_load_dwordx4 v[204:207], v[248:249], off offset:256
	s_mov_b64 s[14:15], 0x30000
	v_lshl_add_u64 v[248:249], v[166:167], 0, s[14:15]
	global_load_dwordx4 v[208:211], v[248:249], off
	global_load_dwordx4 v[212:215], v[248:249], off offset:256
	s_mov_b64 s[14:15], 0x80000
	v_lshl_add_u64 v[248:249], v[166:167], 0, s[14:15]
	global_load_dwordx4 v[216:219], v[248:249], off
	global_load_dwordx4 v[220:223], v[248:249], off offset:256
	s_mov_b64 s[14:15], 0x90000
	v_lshl_add_u64 v[248:249], v[166:167], 0, s[14:15]
	global_load_dwordx4 v[224:227], v[248:249], off
	global_load_dwordx4 v[228:231], v[248:249], off offset:256
	s_mov_b64 s[14:15], 0xa0000
	v_lshl_add_u64 v[248:249], v[166:167], 0, s[14:15]
	global_load_dwordx4 v[232:235], v[248:249], off
	global_load_dwordx4 v[236:239], v[248:249], off offset:256
	s_mov_b64 s[14:15], 0xb0000
	v_lshl_add_u64 v[248:249], v[166:167], 0, s[14:15]
	global_load_dwordx4 v[240:243], v[248:249], off
	global_load_dwordx4 v[244:247], v[248:249], off offset:256
	s_waitcnt vmcnt(14)
	v_lshlrev_b32_e32 v196, 16, v188
	v_and_b32_e32 v197, 0xffff0000, v188
	v_lshlrev_b32_e32 v188, 16, v189
	v_and_b32_e32 v189, 0xffff0000, v189
	v_lshlrev_b32_e32 v198, 16, v190
	v_and_b32_e32 v199, 0xffff0000, v190
	v_lshlrev_b32_e32 v190, 16, v191
	v_and_b32_e32 v191, 0xffff0000, v191
	v_pk_fma_f32 v[130:131], v[130:131], 0.5, v[188:189] op_sel_hi:[1,0,1]
	v_pk_fma_f32 v[128:129], v[128:129], 0.5, v[196:197] op_sel_hi:[1,0,1]
	v_pk_fma_f32 v[188:189], v[124:125], 0.5, v[198:199] op_sel_hi:[1,0,1]
	v_cvt_pk_bf16_f32 v124, v128, v129
	v_cvt_pk_bf16_f32 v125, v130, v131
	v_pk_fma_f32 v[190:191], v[126:127], 0.5, v[190:191] op_sel_hi:[1,0,1]
	v_cvt_pk_bf16_f32 v126, v188, v189
	s_nop 0
	v_cvt_pk_bf16_f32 v127, v190, v191
	global_store_dwordx4 v[166:167], v[124:127], off
	s_nop 1
	v_mul_f32_e32 v124, v128, v128
	v_mul_f32_e32 v125, v130, v130
	v_fmac_f32_e32 v124, v129, v129
	v_fmac_f32_e32 v125, v131, v131
	v_add_f32_e32 v124, v125, v124
	v_mul_f32_e32 v125, v188, v188
	v_mul_f32_e32 v126, v191, v191
	v_fmac_f32_e32 v125, v189, v189
	v_fmac_f32_e32 v126, v190, v190
	v_add_f32_e32 v125, v126, v125
	v_add_f32_e32 v188, v125, v124
	v_lshlrev_b32_e32 v124, 16, v192
	v_and_b32_e32 v125, 0xffff0000, v192
	v_lshlrev_b32_e32 v126, 16, v193
	v_and_b32_e32 v127, 0xffff0000, v193
	v_lshlrev_b32_e32 v128, 16, v194
	v_and_b32_e32 v129, 0xffff0000, v194
	v_lshlrev_b32_e32 v130, 16, v195
	v_and_b32_e32 v131, 0xffff0000, v195
	v_pk_fma_f32 v[122:123], v[122:123], 0.5, v[126:127] op_sel_hi:[1,0,1]
	v_pk_fma_f32 v[120:121], v[120:121], 0.5, v[124:125] op_sel_hi:[1,0,1]
	v_pk_fma_f32 v[124:125], v[116:117], 0.5, v[128:129] op_sel_hi:[1,0,1]
	v_cvt_pk_bf16_f32 v116, v120, v121
	v_cvt_pk_bf16_f32 v117, v122, v123
	v_pk_fma_f32 v[126:127], v[118:119], 0.5, v[130:131] op_sel_hi:[1,0,1]
	v_cvt_pk_bf16_f32 v118, v124, v125
	s_nop 0
	v_cvt_pk_bf16_f32 v119, v126, v127
	global_store_dwordx4 v[166:167], v[116:119], off offset:256
	s_nop 1
	v_mul_f32_e32 v116, v120, v120
	v_mul_f32_e32 v117, v122, v122
	v_fmac_f32_e32 v116, v121, v121
	v_fmac_f32_e32 v117, v123, v123
	v_add_f32_e32 v116, v117, v116
	v_mul_f32_e32 v117, v124, v124
	v_mul_f32_e32 v118, v127, v127
	v_fmac_f32_e32 v117, v125, v125
	v_fmac_f32_e32 v118, v126, v126
	v_add_f32_e32 v117, v118, v117
	v_and_b32_e32 v118, 64, v169
	v_add_f32_e32 v116, v117, v116
	v_xor_b32_e32 v117, 16, v169
	v_add_u32_e32 v118, 64, v118
	v_cmp_lt_i32_e32 vcc, v117, v118
	v_add_f32_e32 v116, v188, v116
	s_nop 0
	v_cndmask_b32_e32 v117, v169, v117, vcc
	v_lshlrev_b32_e32 v128, 2, v117
	v_mov_b32_e32 v117, v116
	s_nop 1
	v_permlane16_swap_b32_e32 v117, v116
	s_waitcnt lgkmcnt(0)
	v_add_f32_e32 v116, v116, v117
	v_xor_b32_e32 v117, 32, v169
	v_cmp_lt_i32_e32 vcc, v117, v118
	s_nop 1
	v_cndmask_b32_e32 v117, v169, v117, vcc
	v_lshlrev_b32_e32 v129, 2, v117
	v_mov_b32_e32 v117, v116
	s_nop 1
	v_permlane32_swap_b32_e32 v117, v116
	s_and_saveexec_b64 s[14:15], s[2:3]
	s_cbranch_execz .LBB0_172
	s_waitcnt lgkmcnt(0)
	v_add_f32_e32 v116, v116, v117
	v_fma_f32 v116, v116, s60, 0.5
	v_cvt_u32_f32_e32 v118, v116
	v_lshl_add_u64 v[116:117], v[160:161], 2, s[8:9]
	global_atomic_add v[116:117], v118, off
; __device__ __forceinline__ unsigned cvt_pk_bf16(float lo, float hi) { unsigned r; asm volatile("v_cvt_pk_bf16_f32 %0, %1, %2" : "=v"(r) : "v"(lo), "v"(hi)); return r; }
;     __device__ __forceinline__ void operator()(const f32x4 (&acc)[2][2][4][2], const Unit& u, int wr, int wc, int fr, int fq, const float (&)[8]) const {
;     ...
;         for (int g = 0; g < 8; ++g) { const int ai = g >> 2, m = g & 3, row = row0 + ai * HALF + m * 16; const size_t off = (size_t)row * 2048 + col0; float ss = 0.f;
;             if (g + 1 < 8) { const size_t offn = (size_t)(row0 + ((g + 1) >> 2) * HALF + ((g + 1) & 3) * 16) * 2048 + col0;
; #pragma unroll
;                 for (int bj = 0; bj < 2; ++bj) xn[bj] = *(const u32x4*)(xb + offn + bj * HALF); }
; #pragma unroll
;             for (int bj = 0; bj < 2; ++bj) { const size_t o = off + bj * HALF; const u32x4 xw = xc[bj];
;                 const f32x4 x0 = (f32x4){__uint_as_float(xw.x << 16), __uint_as_float(xw.x & 0xffff0000u), __uint_as_float(xw.y << 16), __uint_as_float(xw.y & 0xffff0000u)};
;                 const f32x4 x1 = (f32x4){__uint_as_float(xw.z << 16), __uint_as_float(xw.z & 0xffff0000u), __uint_as_float(xw.w << 16), __uint_as_float(xw.w & 0xffff0000u)};
;                 const f32x4 v0 = x0 + acc[ai][bj][m][0] * alpha, v1 = x1 + acc[ai][bj][m][1] * alpha;
;                 if (xf) { *(f32x4*)(xf + o) = v0; *(f32x4*)(xf + o + 4) = v1; }
;                 else { u32x4 w; w.x = cvt_pk_bf16(v0[0], v0[1]); w.y = cvt_pk_bf16(v0[2], v0[3]); w.z = cvt_pk_bf16(v1[0], v1[1]); w.w = cvt_pk_bf16(v1[2], v1[3]); *(u32x4*)(xb + o) = w; }
;                 ss += ((v0[0] * v0[0] + v0[1] * v0[1]) + (v0[2] * v0[2] + v0[3] * v0[3])) + ((v1[0] * v1[0] + v1[1] * v1[1]) + (v1[2] * v1[2] + v1[3] * v1[3])); }
;             ss += __shfl_xor(ss, 16); ss += __shfl_xor(ss, 32);
;             if (fq == 0) (void)__hip_atomic_fetch_add((unsigned*)(ssq_out + row), (unsigned)(ss * SSQ_SCALE + 0.5f), __ATOMIC_RELAXED, __HIP_MEMORY_SCOPE_AGENT);
; #pragma unroll
;             for (int bj = 0; bj < 2; ++bj) xc[bj] = xn[bj]; }
.LBB0_172:
	s_or_b64 exec, exec, s[14:15]
	v_or_b32_e32 v124, 32, v160
	v_ashrrev_i32_e32 v125, 31, v124
	s_waitcnt lgkmcnt(0)
	v_lshlrev_b64 v[116:117], 12, v[124:125]
	v_lshl_add_u64 v[116:117], s[46:47], 0, v[116:117]
	v_lshl_add_u64 v[126:127], v[158:159], 1, v[116:117]
	s_waitcnt vmcnt(12)
	v_mov_b32_e32 v120, v200
	v_mov_b32_e32 v121, v201
	v_mov_b32_e32 v122, v202
	v_mov_b32_e32 v123, v203
	v_mov_b32_e32 v116, v204
	v_mov_b32_e32 v117, v205
	v_mov_b32_e32 v118, v206
	v_mov_b32_e32 v119, v207
	v_lshlrev_b32_e32 v130, 16, v136
	v_and_b32_e32 v131, 0xffff0000, v136
	v_lshlrev_b32_e32 v136, 16, v137
	v_and_b32_e32 v137, 0xffff0000, v137
	v_lshlrev_b32_e32 v166, 16, v138
	v_and_b32_e32 v167, 0xffff0000, v138
	v_lshlrev_b32_e32 v138, 16, v139
	v_and_b32_e32 v139, 0xffff0000, v139
	v_pk_fma_f32 v[114:115], v[114:115], 0.5, v[136:137] op_sel_hi:[1,0,1]
	v_pk_fma_f32 v[112:113], v[112:113], 0.5, v[130:131] op_sel_hi:[1,0,1]
	v_pk_fma_f32 v[136:137], v[110:111], 0.5, v[138:139] op_sel_hi:[1,0,1]
	v_mul_f32_e32 v110, v112, v112
	v_mul_f32_e32 v111, v114, v114
	v_pk_fma_f32 v[130:131], v[108:109], 0.5, v[166:167] op_sel_hi:[1,0,1]
	v_fmac_f32_e32 v110, v113, v113
	v_fmac_f32_e32 v111, v115, v115
	v_cvt_pk_bf16_f32 v108, v112, v113
	v_add_f32_e32 v110, v111, v110
	v_mul_f32_e32 v111, v130, v130
	v_mul_f32_e32 v112, v137, v137
	v_fmac_f32_e32 v111, v131, v131
	v_fmac_f32_e32 v112, v136, v136
	v_add_f32_e32 v111, v112, v111
	v_add_f32_e32 v138, v111, v110
	v_lshlrev_b32_e32 v110, 16, v132
	v_and_b32_e32 v111, 0xffff0000, v132
	v_lshlrev_b32_e32 v112, 16, v133
	v_and_b32_e32 v113, 0xffff0000, v133
	v_cvt_pk_bf16_f32 v109, v114, v115
	v_lshlrev_b32_e32 v114, 16, v134
	v_and_b32_e32 v115, 0xffff0000, v134
	v_pk_fma_f32 v[106:107], v[106:107], 0.5, v[112:113] op_sel_hi:[1,0,1]
	v_pk_fma_f32 v[104:105], v[104:105], 0.5, v[110:111] op_sel_hi:[1,0,1]
	v_lshlrev_b32_e32 v132, 16, v135
	v_and_b32_e32 v133, 0xffff0000, v135
	v_pk_fma_f32 v[112:113], v[100:101], 0.5, v[114:115] op_sel_hi:[1,0,1]
	v_mul_f32_e32 v100, v104, v104
	v_mul_f32_e32 v101, v106, v106
	v_pk_fma_f32 v[114:115], v[102:103], 0.5, v[132:133] op_sel_hi:[1,0,1]
	v_fmac_f32_e32 v100, v105, v105
	v_fmac_f32_e32 v101, v107, v107
	v_add_f32_e32 v100, v101, v100
	v_mul_f32_e32 v101, v112, v112
	v_mul_f32_e32 v102, v115, v115
	v_fmac_f32_e32 v101, v113, v113
	v_fmac_f32_e32 v102, v114, v114
	v_add_f32_e32 v101, v102, v101
	v_add_f32_e32 v100, v101, v100
	v_add_f32_e32 v100, v138, v100
	v_mov_b32_e32 v101, v100
	s_nop 1
	v_permlane16_swap_b32_e32 v101, v100
	v_cvt_pk_bf16_f32 v110, v130, v131
	v_cvt_pk_bf16_f32 v111, v136, v137
	global_store_dwordx4 v[164:165], v[108:111], off
	v_cvt_pk_bf16_f32 v102, v104, v105
	s_waitcnt lgkmcnt(0)
	v_add_f32_e32 v100, v100, v101
	v_mov_b32_e32 v101, v100
	s_nop 1
	v_permlane32_swap_b32_e32 v101, v100
	v_cvt_pk_bf16_f32 v103, v106, v107
	v_cvt_pk_bf16_f32 v104, v112, v113
	v_cvt_pk_bf16_f32 v105, v114, v115
	global_store_dwordx4 v[164:165], v[102:105], off offset:256
	s_and_saveexec_b64 s[14:15], s[2:3]
	s_cbranch_execz .LBB0_174
	s_waitcnt lgkmcnt(0)
	v_add_f32_e32 v100, v100, v101
	v_fma_f32 v100, v100, s60, 0.5
	v_cvt_u32_f32_e32 v102, v100
	v_lshl_add_u64 v[100:101], v[162:163], 2, s[8:9]
	global_atomic_add v[100:101], v102, off
.LBB0_174:
	s_or_b64 exec, exec, s[14:15]
	v_or_b32_e32 v108, 48, v160
	v_ashrrev_i32_e32 v109, 31, v108
	s_waitcnt lgkmcnt(0)
	v_lshlrev_b64 v[100:101], 12, v[108:109]
	v_lshl_add_u64 v[100:101], s[46:47], 0, v[100:101]
	v_lshl_add_u64 v[110:111], v[158:159], 1, v[100:101]
	s_waitcnt vmcnt(12)
	v_mov_b32_e32 v104, v208
	v_mov_b32_e32 v105, v209
	v_mov_b32_e32 v106, v210
	v_mov_b32_e32 v107, v211
	v_mov_b32_e32 v100, v212
	v_mov_b32_e32 v101, v213
	v_mov_b32_e32 v102, v214
	v_mov_b32_e32 v103, v215
	v_lshlrev_b32_e32 v112, 16, v120
	v_and_b32_e32 v113, 0xffff0000, v120
	v_lshlrev_b32_e32 v114, 16, v121
	v_and_b32_e32 v115, 0xffff0000, v121
	v_lshlrev_b32_e32 v120, 16, v122
	v_and_b32_e32 v121, 0xffff0000, v122
	v_lshlrev_b32_e32 v122, 16, v123
	v_and_b32_e32 v123, 0xffff0000, v123
	v_pk_fma_f32 v[98:99], v[98:99], 0.5, v[114:115] op_sel_hi:[1,0,1]
	v_pk_fma_f32 v[96:97], v[96:97], 0.5, v[112:113] op_sel_hi:[1,0,1]
	v_pk_fma_f32 v[114:115], v[94:95], 0.5, v[122:123] op_sel_hi:[1,0,1]
	v_mul_f32_e32 v94, v96, v96
	v_mul_f32_e32 v95, v98, v98
	v_pk_fma_f32 v[112:113], v[92:93], 0.5, v[120:121] op_sel_hi:[1,0,1]
	v_fmac_f32_e32 v94, v97, v97
	v_fmac_f32_e32 v95, v99, v99
	v_cvt_pk_bf16_f32 v92, v96, v97
	v_add_f32_e32 v94, v95, v94
	v_mul_f32_e32 v95, v112, v112
	v_mul_f32_e32 v96, v115, v115
	v_fmac_f32_e32 v95, v113, v113
	v_fmac_f32_e32 v96, v114, v114
	v_add_f32_e32 v95, v96, v95
	v_add_f32_e32 v120, v95, v94
	v_lshlrev_b32_e32 v94, 16, v116
	v_and_b32_e32 v95, 0xffff0000, v116
	v_lshlrev_b32_e32 v96, 16, v117
	v_and_b32_e32 v97, 0xffff0000, v117
	v_cvt_pk_bf16_f32 v93, v98, v99
	v_lshlrev_b32_e32 v98, 16, v118
	v_and_b32_e32 v99, 0xffff0000, v118
	v_pk_fma_f32 v[90:91], v[90:91], 0.5, v[96:97] op_sel_hi:[1,0,1]
	v_pk_fma_f32 v[88:89], v[88:89], 0.5, v[94:95] op_sel_hi:[1,0,1]
	v_lshlrev_b32_e32 v116, 16, v119
	v_and_b32_e32 v117, 0xffff0000, v119
	v_pk_fma_f32 v[96:97], v[84:85], 0.5, v[98:99] op_sel_hi:[1,0,1]
	v_mul_f32_e32 v84, v88, v88
	v_mul_f32_e32 v85, v90, v90
	v_pk_fma_f32 v[98:99], v[86:87], 0.5, v[116:117] op_sel_hi:[1,0,1]
	v_fmac_f32_e32 v84, v89, v89
	v_fmac_f32_e32 v85, v91, v91
	v_add_f32_e32 v84, v85, v84
	v_mul_f32_e32 v85, v96, v96
	v_mul_f32_e32 v86, v99, v99
	v_fmac_f32_e32 v85, v97, v97
	v_fmac_f32_e32 v86, v98, v98
	v_add_f32_e32 v85, v86, v85
	v_add_f32_e32 v84, v85, v84
	v_add_f32_e32 v84, v120, v84
	v_mov_b32_e32 v85, v84
	s_nop 1
	v_permlane16_swap_b32_e32 v85, v84
	v_cvt_pk_bf16_f32 v94, v112, v113
	v_cvt_pk_bf16_f32 v95, v114, v115
	global_store_dwordx4 v[126:127], v[92:95], off
	v_cvt_pk_bf16_f32 v86, v88, v89
	s_waitcnt lgkmcnt(0)
	v_add_f32_e32 v84, v84, v85
	v_mov_b32_e32 v85, v84
	s_nop 1
	v_permlane32_swap_b32_e32 v85, v84
	v_cvt_pk_bf16_f32 v87, v90, v91
	v_cvt_pk_bf16_f32 v88, v96, v97
	v_cvt_pk_bf16_f32 v89, v98, v99
	global_store_dwordx4 v[126:127], v[86:89], off offset:256
	s_and_saveexec_b64 s[14:15], s[2:3]
	s_cbranch_execz .LBB0_176
	s_waitcnt lgkmcnt(0)
	v_add_f32_e32 v84, v84, v85
	v_fma_f32 v84, v84, s60, 0.5
	v_cvt_u32_f32_e32 v86, v84
	v_lshl_add_u64 v[84:85], v[124:125], 2, s[8:9]
	global_atomic_add v[84:85], v86, off
; __device__ __forceinline__ unsigned cvt_pk_bf16(float lo, float hi) { unsigned r; asm volatile("v_cvt_pk_bf16_f32 %0, %1, %2" : "=v"(r) : "v"(lo), "v"(hi)); return r; }
;     __device__ __forceinline__ void operator()(const f32x4 (&acc)[2][2][4][2], const Unit& u, int wr, int wc, int fr, int fq, const float (&)[8]) const {
;     ...
;         for (int g = 0; g < 8; ++g) { const int ai = g >> 2, m = g & 3, row = row0 + ai * HALF + m * 16; const size_t off = (size_t)row * 2048 + col0; float ss = 0.f;
;             if (g + 1 < 8) { const size_t offn = (size_t)(row0 + ((g + 1) >> 2) * HALF + ((g + 1) & 3) * 16) * 2048 + col0;
; #pragma unroll
;                 for (int bj = 0; bj < 2; ++bj) xn[bj] = *(const u32x4*)(xb + offn + bj * HALF); }
; #pragma unroll
;             for (int bj = 0; bj < 2; ++bj) { const size_t o = off + bj * HALF; const u32x4 xw = xc[bj];
;                 const f32x4 x0 = (f32x4){__uint_as_float(xw.x << 16), __uint_as_float(xw.x & 0xffff0000u), __uint_as_float(xw.y << 16), __uint_as_float(xw.y & 0xffff0000u)};
;                 const f32x4 x1 = (f32x4){__uint_as_float(xw.z << 16), __uint_as_float(xw.z & 0xffff0000u), __uint_as_float(xw.w << 16), __uint_as_float(xw.w & 0xffff0000u)};
;                 const f32x4 v0 = x0 + acc[ai][bj][m][0] * alpha, v1 = x1 + acc[ai][bj][m][1] * alpha;
;                 if (xf) { *(f32x4*)(xf + o) = v0; *(f32x4*)(xf + o + 4) = v1; }
;                 else { u32x4 w; w.x = cvt_pk_bf16(v0[0], v0[1]); w.y = cvt_pk_bf16(v0[2], v0[3]); w.z = cvt_pk_bf16(v1[0], v1[1]); w.w = cvt_pk_bf16(v1[2], v1[3]); *(u32x4*)(xb + o) = w; }
;                 ss += ((v0[0] * v0[0] + v0[1] * v0[1]) + (v0[2] * v0[2] + v0[3] * v0[3])) + ((v1[0] * v1[0] + v1[1] * v1[1]) + (v1[2] * v1[2] + v1[3] * v1[3])); }
;             ss += __shfl_xor(ss, 16); ss += __shfl_xor(ss, 32);
;             if (fq == 0) (void)__hip_atomic_fetch_add((unsigned*)(ssq_out + row), (unsigned)(ss * SSQ_SCALE + 0.5f), __ATOMIC_RELAXED, __HIP_MEMORY_SCOPE_AGENT);
; #pragma unroll
;             for (int bj = 0; bj < 2; ++bj) xc[bj] = xn[bj]; }
.LBB0_176:
	s_or_b64 exec, exec, s[14:15]
	v_add_u32_e32 v92, 0x80, v160
	v_ashrrev_i32_e32 v93, 31, v92
	s_waitcnt lgkmcnt(0)
	v_lshlrev_b64 v[84:85], 12, v[92:93]
	v_lshl_add_u64 v[84:85], s[46:47], 0, v[84:85]
	v_lshl_add_u64 v[94:95], v[158:159], 1, v[84:85]
	s_waitcnt vmcnt(12)
	v_mov_b32_e32 v88, v216
	v_mov_b32_e32 v89, v217
	v_mov_b32_e32 v90, v218
	v_mov_b32_e32 v91, v219
	v_mov_b32_e32 v84, v220
	v_mov_b32_e32 v85, v221
	v_mov_b32_e32 v86, v222
	v_mov_b32_e32 v87, v223
	v_lshlrev_b32_e32 v96, 16, v104
	v_and_b32_e32 v97, 0xffff0000, v104
	v_lshlrev_b32_e32 v98, 16, v105
	v_and_b32_e32 v99, 0xffff0000, v105
	v_lshlrev_b32_e32 v104, 16, v106
	v_and_b32_e32 v105, 0xffff0000, v106
	v_lshlrev_b32_e32 v106, 16, v107
	v_and_b32_e32 v107, 0xffff0000, v107
	v_pk_fma_f32 v[82:83], v[82:83], 0.5, v[98:99] op_sel_hi:[1,0,1]
	v_pk_fma_f32 v[80:81], v[80:81], 0.5, v[96:97] op_sel_hi:[1,0,1]
	v_pk_fma_f32 v[98:99], v[78:79], 0.5, v[106:107] op_sel_hi:[1,0,1]
	v_mul_f32_e32 v78, v80, v80
	v_mul_f32_e32 v79, v82, v82
	v_pk_fma_f32 v[96:97], v[76:77], 0.5, v[104:105] op_sel_hi:[1,0,1]
	v_fmac_f32_e32 v78, v81, v81
	v_fmac_f32_e32 v79, v83, v83
	v_cvt_pk_bf16_f32 v76, v80, v81
	v_add_f32_e32 v78, v79, v78
	v_mul_f32_e32 v79, v96, v96
	v_mul_f32_e32 v80, v99, v99
	v_fmac_f32_e32 v79, v97, v97
	v_fmac_f32_e32 v80, v98, v98
	v_add_f32_e32 v79, v80, v79
	v_add_f32_e32 v104, v79, v78
	v_lshlrev_b32_e32 v78, 16, v100
	v_and_b32_e32 v79, 0xffff0000, v100
	v_lshlrev_b32_e32 v80, 16, v101
	v_and_b32_e32 v81, 0xffff0000, v101
	v_cvt_pk_bf16_f32 v77, v82, v83
	v_lshlrev_b32_e32 v82, 16, v102
	v_and_b32_e32 v83, 0xffff0000, v102
	v_pk_fma_f32 v[74:75], v[74:75], 0.5, v[80:81] op_sel_hi:[1,0,1]
	v_pk_fma_f32 v[72:73], v[72:73], 0.5, v[78:79] op_sel_hi:[1,0,1]
	v_lshlrev_b32_e32 v100, 16, v103
	v_and_b32_e32 v101, 0xffff0000, v103
	v_pk_fma_f32 v[80:81], v[68:69], 0.5, v[82:83] op_sel_hi:[1,0,1]
	v_mul_f32_e32 v68, v72, v72
	v_mul_f32_e32 v69, v74, v74
	v_pk_fma_f32 v[82:83], v[70:71], 0.5, v[100:101] op_sel_hi:[1,0,1]
	v_fmac_f32_e32 v68, v73, v73
	v_fmac_f32_e32 v69, v75, v75
	v_add_f32_e32 v68, v69, v68
	v_mul_f32_e32 v69, v80, v80
	v_mul_f32_e32 v70, v83, v83
	v_fmac_f32_e32 v69, v81, v81
	v_fmac_f32_e32 v70, v82, v82
	v_add_f32_e32 v69, v70, v69
	v_add_f32_e32 v68, v69, v68
	v_add_f32_e32 v68, v104, v68
	v_mov_b32_e32 v69, v68
	s_nop 1
	v_permlane16_swap_b32_e32 v69, v68
	v_cvt_pk_bf16_f32 v78, v96, v97
	v_cvt_pk_bf16_f32 v79, v98, v99
	global_store_dwordx4 v[110:111], v[76:79], off
	v_cvt_pk_bf16_f32 v70, v72, v73
	s_waitcnt lgkmcnt(0)
	v_add_f32_e32 v68, v68, v69
	v_mov_b32_e32 v69, v68
	s_nop 1
	v_permlane32_swap_b32_e32 v69, v68
	v_cvt_pk_bf16_f32 v71, v74, v75
	v_cvt_pk_bf16_f32 v72, v80, v81
	v_cvt_pk_bf16_f32 v73, v82, v83
	global_store_dwordx4 v[110:111], v[70:73], off offset:256
	s_and_saveexec_b64 s[14:15], s[2:3]
	s_cbranch_execz .LBB0_178
	s_waitcnt lgkmcnt(0)
	v_add_f32_e32 v68, v68, v69
	v_fma_f32 v68, v68, s60, 0.5
	v_cvt_u32_f32_e32 v70, v68
	v_lshl_add_u64 v[68:69], v[108:109], 2, s[8:9]
	global_atomic_add v[68:69], v70, off
.LBB0_178:
	s_or_b64 exec, exec, s[14:15]
	v_or_b32_e32 v76, 16, v92
	v_ashrrev_i32_e32 v77, 31, v76
	s_waitcnt lgkmcnt(0)
	v_lshlrev_b64 v[68:69], 12, v[76:77]
	v_lshl_add_u64 v[68:69], s[46:47], 0, v[68:69]
	v_lshl_add_u64 v[78:79], v[158:159], 1, v[68:69]
	s_waitcnt vmcnt(12)
	v_mov_b32_e32 v72, v224
	v_mov_b32_e32 v73, v225
	v_mov_b32_e32 v74, v226
	v_mov_b32_e32 v75, v227
	v_mov_b32_e32 v68, v228
	v_mov_b32_e32 v69, v229
	v_mov_b32_e32 v70, v230
	v_mov_b32_e32 v71, v231
	v_lshlrev_b32_e32 v80, 16, v88
	v_and_b32_e32 v81, 0xffff0000, v88
	v_lshlrev_b32_e32 v82, 16, v89
	v_and_b32_e32 v83, 0xffff0000, v89
	v_lshlrev_b32_e32 v88, 16, v90
	v_and_b32_e32 v89, 0xffff0000, v90
	v_lshlrev_b32_e32 v90, 16, v91
	v_and_b32_e32 v91, 0xffff0000, v91
	v_pk_fma_f32 v[66:67], v[66:67], 0.5, v[82:83] op_sel_hi:[1,0,1]
	v_pk_fma_f32 v[64:65], v[64:65], 0.5, v[80:81] op_sel_hi:[1,0,1]
	v_pk_fma_f32 v[82:83], v[62:63], 0.5, v[90:91] op_sel_hi:[1,0,1]
	v_mul_f32_e32 v62, v64, v64
	v_mul_f32_e32 v63, v66, v66
	v_pk_fma_f32 v[80:81], v[60:61], 0.5, v[88:89] op_sel_hi:[1,0,1]
	v_fmac_f32_e32 v62, v65, v65
	v_fmac_f32_e32 v63, v67, v67
	v_cvt_pk_bf16_f32 v60, v64, v65
	v_add_f32_e32 v62, v63, v62
	v_mul_f32_e32 v63, v80, v80
	v_mul_f32_e32 v64, v83, v83
	v_fmac_f32_e32 v63, v81, v81
	v_fmac_f32_e32 v64, v82, v82
	v_add_f32_e32 v63, v64, v63
	v_add_f32_e32 v88, v63, v62
	v_lshlrev_b32_e32 v62, 16, v84
	v_and_b32_e32 v63, 0xffff0000, v84
	v_lshlrev_b32_e32 v64, 16, v85
	v_and_b32_e32 v65, 0xffff0000, v85
	v_cvt_pk_bf16_f32 v61, v66, v67
	v_lshlrev_b32_e32 v66, 16, v86
	v_and_b32_e32 v67, 0xffff0000, v86
	v_pk_fma_f32 v[58:59], v[58:59], 0.5, v[64:65] op_sel_hi:[1,0,1]
	v_pk_fma_f32 v[56:57], v[56:57], 0.5, v[62:63] op_sel_hi:[1,0,1]
	v_lshlrev_b32_e32 v84, 16, v87
	v_and_b32_e32 v85, 0xffff0000, v87
	v_pk_fma_f32 v[64:65], v[52:53], 0.5, v[66:67] op_sel_hi:[1,0,1]
	v_mul_f32_e32 v52, v56, v56
	v_mul_f32_e32 v53, v58, v58
	v_pk_fma_f32 v[66:67], v[54:55], 0.5, v[84:85] op_sel_hi:[1,0,1]
	v_fmac_f32_e32 v52, v57, v57
	v_fmac_f32_e32 v53, v59, v59
	v_add_f32_e32 v52, v53, v52
	v_mul_f32_e32 v53, v64, v64
	v_mul_f32_e32 v54, v67, v67
	v_fmac_f32_e32 v53, v65, v65
	v_fmac_f32_e32 v54, v66, v66
	v_add_f32_e32 v53, v54, v53
	v_add_f32_e32 v52, v53, v52
	v_add_f32_e32 v52, v88, v52
	v_mov_b32_e32 v53, v52
	s_nop 1
	v_permlane16_swap_b32_e32 v53, v52
	v_cvt_pk_bf16_f32 v62, v80, v81
	v_cvt_pk_bf16_f32 v63, v82, v83
	global_store_dwordx4 v[94:95], v[60:63], off
	v_cvt_pk_bf16_f32 v54, v56, v57
	s_waitcnt lgkmcnt(0)
	v_add_f32_e32 v52, v52, v53
	v_mov_b32_e32 v53, v52
	s_nop 1
	v_permlane32_swap_b32_e32 v53, v52
	v_cvt_pk_bf16_f32 v55, v58, v59
	v_cvt_pk_bf16_f32 v56, v64, v65
	v_cvt_pk_bf16_f32 v57, v66, v67
	global_store_dwordx4 v[94:95], v[54:57], off offset:256
	s_and_saveexec_b64 s[14:15], s[2:3]
	s_cbranch_execz .LBB0_180
	s_waitcnt lgkmcnt(0)
	v_add_f32_e32 v52, v52, v53
	v_fma_f32 v52, v52, s60, 0.5
	v_cvt_u32_f32_e32 v54, v52
	v_lshl_add_u64 v[52:53], v[92:93], 2, s[8:9]
	global_atomic_add v[52:53], v54, off
; __device__ __forceinline__ unsigned cvt_pk_bf16(float lo, float hi) { unsigned r; asm volatile("v_cvt_pk_bf16_f32 %0, %1, %2" : "=v"(r) : "v"(lo), "v"(hi)); return r; }
;     __device__ __forceinline__ void operator()(const f32x4 (&acc)[2][2][4][2], const Unit& u, int wr, int wc, int fr, int fq, const float (&)[8]) const {
;     ...
;         for (int g = 0; g < 8; ++g) { const int ai = g >> 2, m = g & 3, row = row0 + ai * HALF + m * 16; const size_t off = (size_t)row * 2048 + col0; float ss = 0.f;
;             if (g + 1 < 8) { const size_t offn = (size_t)(row0 + ((g + 1) >> 2) * HALF + ((g + 1) & 3) * 16) * 2048 + col0;
; #pragma unroll
;                 for (int bj = 0; bj < 2; ++bj) xn[bj] = *(const u32x4*)(xb + offn + bj * HALF); }
; #pragma unroll
;             for (int bj = 0; bj < 2; ++bj) { const size_t o = off + bj * HALF; const u32x4 xw = xc[bj];
;                 const f32x4 x0 = (f32x4){__uint_as_float(xw.x << 16), __uint_as_float(xw.x & 0xffff0000u), __uint_as_float(xw.y << 16), __uint_as_float(xw.y & 0xffff0000u)};
;                 const f32x4 x1 = (f32x4){__uint_as_float(xw.z << 16), __uint_as_float(xw.z & 0xffff0000u), __uint_as_float(xw.w << 16), __uint_as_float(xw.w & 0xffff0000u)};
;                 const f32x4 v0 = x0 + acc[ai][bj][m][0] * alpha, v1 = x1 + acc[ai][bj][m][1] * alpha;
;                 if (xf) { *(f32x4*)(xf + o) = v0; *(f32x4*)(xf + o + 4) = v1; }
;                 else { u32x4 w; w.x = cvt_pk_bf16(v0[0], v0[1]); w.y = cvt_pk_bf16(v0[2], v0[3]); w.z = cvt_pk_bf16(v1[0], v1[1]); w.w = cvt_pk_bf16(v1[2], v1[3]); *(u32x4*)(xb + o) = w; }
;                 ss += ((v0[0] * v0[0] + v0[1] * v0[1]) + (v0[2] * v0[2] + v0[3] * v0[3])) + ((v1[0] * v1[0] + v1[1] * v1[1]) + (v1[2] * v1[2] + v1[3] * v1[3])); }
;             ss += __shfl_xor(ss, 16); ss += __shfl_xor(ss, 32);
;             if (fq == 0) (void)__hip_atomic_fetch_add((unsigned*)(ssq_out + row), (unsigned)(ss * SSQ_SCALE + 0.5f), __ATOMIC_RELAXED, __HIP_MEMORY_SCOPE_AGENT);
; #pragma unroll
;             for (int bj = 0; bj < 2; ++bj) xc[bj] = xn[bj]; }
.LBB0_180:
	s_or_b64 exec, exec, s[14:15]
	v_or_b32_e32 v60, 32, v92
	v_ashrrev_i32_e32 v61, 31, v60
	s_waitcnt lgkmcnt(0)
	v_lshlrev_b64 v[52:53], 12, v[60:61]
	v_lshl_add_u64 v[52:53], s[46:47], 0, v[52:53]
	v_lshl_add_u64 v[62:63], v[158:159], 1, v[52:53]
	s_waitcnt vmcnt(12)
	v_mov_b32_e32 v56, v232
	v_mov_b32_e32 v57, v233
	v_mov_b32_e32 v58, v234
	v_mov_b32_e32 v59, v235
	v_mov_b32_e32 v52, v236
	v_mov_b32_e32 v53, v237
	v_mov_b32_e32 v54, v238
	v_mov_b32_e32 v55, v239
	v_lshlrev_b32_e32 v64, 16, v72
	v_and_b32_e32 v65, 0xffff0000, v72
	v_lshlrev_b32_e32 v66, 16, v73
	v_and_b32_e32 v67, 0xffff0000, v73
	v_lshlrev_b32_e32 v72, 16, v74
	v_and_b32_e32 v73, 0xffff0000, v74
	v_lshlrev_b32_e32 v74, 16, v75
	v_and_b32_e32 v75, 0xffff0000, v75
	v_pk_fma_f32 v[50:51], v[50:51], 0.5, v[66:67] op_sel_hi:[1,0,1]
	v_pk_fma_f32 v[48:49], v[48:49], 0.5, v[64:65] op_sel_hi:[1,0,1]
	v_pk_fma_f32 v[66:67], v[46:47], 0.5, v[74:75] op_sel_hi:[1,0,1]
	v_mul_f32_e32 v46, v48, v48
	v_mul_f32_e32 v47, v50, v50
	v_pk_fma_f32 v[64:65], v[44:45], 0.5, v[72:73] op_sel_hi:[1,0,1]
	v_fmac_f32_e32 v46, v49, v49
	v_fmac_f32_e32 v47, v51, v51
	v_cvt_pk_bf16_f32 v44, v48, v49
	v_add_f32_e32 v46, v47, v46
	v_mul_f32_e32 v47, v64, v64
	v_mul_f32_e32 v48, v67, v67
	v_fmac_f32_e32 v47, v65, v65
	v_fmac_f32_e32 v48, v66, v66
	v_add_f32_e32 v47, v48, v47
	v_add_f32_e32 v72, v47, v46
	v_lshlrev_b32_e32 v46, 16, v68
	v_and_b32_e32 v47, 0xffff0000, v68
	v_lshlrev_b32_e32 v48, 16, v69
	v_and_b32_e32 v49, 0xffff0000, v69
	v_cvt_pk_bf16_f32 v45, v50, v51
	v_lshlrev_b32_e32 v50, 16, v70
	v_and_b32_e32 v51, 0xffff0000, v70
	v_pk_fma_f32 v[42:43], v[42:43], 0.5, v[48:49] op_sel_hi:[1,0,1]
	v_pk_fma_f32 v[40:41], v[40:41], 0.5, v[46:47] op_sel_hi:[1,0,1]
	v_lshlrev_b32_e32 v68, 16, v71
	v_and_b32_e32 v69, 0xffff0000, v71
	v_pk_fma_f32 v[48:49], v[36:37], 0.5, v[50:51] op_sel_hi:[1,0,1]
	v_mul_f32_e32 v36, v40, v40
	v_mul_f32_e32 v37, v42, v42
	v_pk_fma_f32 v[50:51], v[38:39], 0.5, v[68:69] op_sel_hi:[1,0,1]
	v_fmac_f32_e32 v36, v41, v41
	v_fmac_f32_e32 v37, v43, v43
	v_add_f32_e32 v36, v37, v36
	v_mul_f32_e32 v37, v48, v48
	v_mul_f32_e32 v38, v51, v51
	v_fmac_f32_e32 v37, v49, v49
	v_fmac_f32_e32 v38, v50, v50
	v_add_f32_e32 v37, v38, v37
	v_add_f32_e32 v36, v37, v36
	v_add_f32_e32 v36, v72, v36
	v_mov_b32_e32 v37, v36
	s_nop 1
	v_permlane16_swap_b32_e32 v37, v36
	v_cvt_pk_bf16_f32 v46, v64, v65
	v_cvt_pk_bf16_f32 v47, v66, v67
	global_store_dwordx4 v[78:79], v[44:47], off
	v_cvt_pk_bf16_f32 v38, v40, v41
	s_waitcnt lgkmcnt(0)
	v_add_f32_e32 v36, v36, v37
	v_mov_b32_e32 v37, v36
	s_nop 1
	v_permlane32_swap_b32_e32 v37, v36
	v_cvt_pk_bf16_f32 v39, v42, v43
	v_cvt_pk_bf16_f32 v40, v48, v49
	v_cvt_pk_bf16_f32 v41, v50, v51
	global_store_dwordx4 v[78:79], v[38:41], off offset:256
	s_and_saveexec_b64 s[14:15], s[2:3]
	s_cbranch_execz .LBB0_182
	s_waitcnt lgkmcnt(0)
	v_add_f32_e32 v36, v36, v37
	v_fma_f32 v36, v36, s60, 0.5
	v_cvt_u32_f32_e32 v38, v36
	v_lshl_add_u64 v[36:37], v[76:77], 2, s[8:9]
	global_atomic_add v[36:37], v38, off
; __device__ __forceinline__ unsigned cvt_pk_bf16(float lo, float hi) { unsigned r; asm volatile("v_cvt_pk_bf16_f32 %0, %1, %2" : "=v"(r) : "v"(lo), "v"(hi)); return r; }
;     __device__ __forceinline__ void operator()(const f32x4 (&acc)[2][2][4][2], const Unit& u, int wr, int wc, int fr, int fq, const float (&)[8]) const {
;     ...
;         for (int g = 0; g < 8; ++g) { const int ai = g >> 2, m = g & 3, row = row0 + ai * HALF + m * 16; const size_t off = (size_t)row * 2048 + col0; float ss = 0.f;
;             if (g + 1 < 8) { const size_t offn = (size_t)(row0 + ((g + 1) >> 2) * HALF + ((g + 1) & 3) * 16) * 2048 + col0;
; #pragma unroll
;                 for (int bj = 0; bj < 2; ++bj) xn[bj] = *(const u32x4*)(xb + offn + bj * HALF); }
; #pragma unroll
;             for (int bj = 0; bj < 2; ++bj) { const size_t o = off + bj * HALF; const u32x4 xw = xc[bj];
;                 const f32x4 x0 = (f32x4){__uint_as_float(xw.x << 16), __uint_as_float(xw.x & 0xffff0000u), __uint_as_float(xw.y << 16), __uint_as_float(xw.y & 0xffff0000u)};
;                 const f32x4 x1 = (f32x4){__uint_as_float(xw.z << 16), __uint_as_float(xw.z & 0xffff0000u), __uint_as_float(xw.w << 16), __uint_as_float(xw.w & 0xffff0000u)};
;                 const f32x4 v0 = x0 + acc[ai][bj][m][0] * alpha, v1 = x1 + acc[ai][bj][m][1] * alpha;
;                 if (xf) { *(f32x4*)(xf + o) = v0; *(f32x4*)(xf + o + 4) = v1; }
;                 else { u32x4 w; w.x = cvt_pk_bf16(v0[0], v0[1]); w.y = cvt_pk_bf16(v0[2], v0[3]); w.z = cvt_pk_bf16(v1[0], v1[1]); w.w = cvt_pk_bf16(v1[2], v1[3]); *(u32x4*)(xb + o) = w; }
;                 ss += ((v0[0] * v0[0] + v0[1] * v0[1]) + (v0[2] * v0[2] + v0[3] * v0[3])) + ((v1[0] * v1[0] + v1[1] * v1[1]) + (v1[2] * v1[2] + v1[3] * v1[3])); }
;             ss += __shfl_xor(ss, 16); ss += __shfl_xor(ss, 32);
;             if (fq == 0) (void)__hip_atomic_fetch_add((unsigned*)(ssq_out + row), (unsigned)(ss * SSQ_SCALE + 0.5f), __ATOMIC_RELAXED, __HIP_MEMORY_SCOPE_AGENT);
; #pragma unroll
;             for (int bj = 0; bj < 2; ++bj) xc[bj] = xn[bj]; }
.LBB0_182:
	s_or_b64 exec, exec, s[14:15]
	v_or_b32_e32 v44, 48, v92
	v_ashrrev_i32_e32 v45, 31, v44
	s_waitcnt lgkmcnt(0)
	v_lshlrev_b64 v[36:37], 12, v[44:45]
	v_lshl_add_u64 v[36:37], s[46:47], 0, v[36:37]
	v_lshl_add_u64 v[46:47], v[158:159], 1, v[36:37]
	s_waitcnt vmcnt(12)
	v_mov_b32_e32 v40, v240
	v_mov_b32_e32 v41, v241
	v_mov_b32_e32 v42, v242
	v_mov_b32_e32 v43, v243
	v_mov_b32_e32 v36, v244
	v_mov_b32_e32 v37, v245
	v_mov_b32_e32 v38, v246
	v_mov_b32_e32 v39, v247
	v_lshlrev_b32_e32 v48, 16, v56
	v_and_b32_e32 v49, 0xffff0000, v56
	v_lshlrev_b32_e32 v50, 16, v57
	v_and_b32_e32 v51, 0xffff0000, v57
	v_lshlrev_b32_e32 v56, 16, v58
	v_and_b32_e32 v57, 0xffff0000, v58
	v_lshlrev_b32_e32 v58, 16, v59
	v_and_b32_e32 v59, 0xffff0000, v59
	v_pk_fma_f32 v[34:35], v[34:35], 0.5, v[50:51] op_sel_hi:[1,0,1]
	v_pk_fma_f32 v[32:33], v[32:33], 0.5, v[48:49] op_sel_hi:[1,0,1]
	v_pk_fma_f32 v[50:51], v[30:31], 0.5, v[58:59] op_sel_hi:[1,0,1]
	v_mul_f32_e32 v30, v32, v32
	v_mul_f32_e32 v31, v34, v34
	v_pk_fma_f32 v[48:49], v[28:29], 0.5, v[56:57] op_sel_hi:[1,0,1]
	v_fmac_f32_e32 v30, v33, v33
	v_fmac_f32_e32 v31, v35, v35
	v_cvt_pk_bf16_f32 v28, v32, v33
	v_add_f32_e32 v30, v31, v30
	v_mul_f32_e32 v31, v48, v48
	v_mul_f32_e32 v32, v51, v51
	v_fmac_f32_e32 v31, v49, v49
	v_fmac_f32_e32 v32, v50, v50
	v_add_f32_e32 v31, v32, v31
	v_add_f32_e32 v56, v31, v30
	v_lshlrev_b32_e32 v30, 16, v52
	v_and_b32_e32 v31, 0xffff0000, v52
	v_lshlrev_b32_e32 v32, 16, v53
	v_and_b32_e32 v33, 0xffff0000, v53
	v_cvt_pk_bf16_f32 v29, v34, v35
	v_lshlrev_b32_e32 v34, 16, v54
	v_and_b32_e32 v35, 0xffff0000, v54
	v_pk_fma_f32 v[26:27], v[26:27], 0.5, v[32:33] op_sel_hi:[1,0,1]
	v_pk_fma_f32 v[24:25], v[24:25], 0.5, v[30:31] op_sel_hi:[1,0,1]
	v_lshlrev_b32_e32 v52, 16, v55
	v_and_b32_e32 v53, 0xffff0000, v55
	v_pk_fma_f32 v[32:33], v[20:21], 0.5, v[34:35] op_sel_hi:[1,0,1]
	v_mul_f32_e32 v20, v24, v24
	v_mul_f32_e32 v21, v26, v26
	v_pk_fma_f32 v[34:35], v[22:23], 0.5, v[52:53] op_sel_hi:[1,0,1]
	v_fmac_f32_e32 v20, v25, v25
	v_fmac_f32_e32 v21, v27, v27
	v_add_f32_e32 v20, v21, v20
	v_mul_f32_e32 v21, v32, v32
	v_mul_f32_e32 v22, v35, v35
	v_fmac_f32_e32 v21, v33, v33
	v_fmac_f32_e32 v22, v34, v34
	v_add_f32_e32 v21, v22, v21
	v_add_f32_e32 v20, v21, v20
	v_add_f32_e32 v20, v56, v20
	v_mov_b32_e32 v21, v20
	s_nop 1
	v_permlane16_swap_b32_e32 v21, v20
	v_cvt_pk_bf16_f32 v30, v48, v49
	v_cvt_pk_bf16_f32 v31, v50, v51
	global_store_dwordx4 v[62:63], v[28:31], off
	v_cvt_pk_bf16_f32 v22, v24, v25
	s_waitcnt lgkmcnt(0)
	v_add_f32_e32 v20, v20, v21
	v_mov_b32_e32 v21, v20
	s_nop 1
	v_permlane32_swap_b32_e32 v21, v20
	v_cvt_pk_bf16_f32 v23, v26, v27
	v_cvt_pk_bf16_f32 v24, v32, v33
	v_cvt_pk_bf16_f32 v25, v34, v35
	global_store_dwordx4 v[62:63], v[22:25], off offset:256
	s_and_saveexec_b64 s[14:15], s[2:3]
	s_cbranch_execz .LBB0_184
	s_waitcnt lgkmcnt(0)
	v_add_f32_e32 v20, v20, v21
	v_fma_f32 v20, v20, s60, 0.5
	v_cvt_u32_f32_e32 v22, v20
	v_lshl_add_u64 v[20:21], v[60:61], 2, s[8:9]
	global_atomic_add v[20:21], v22, off
.LBB0_184:
	s_or_b64 exec, exec, s[14:15]
	v_lshlrev_b32_e32 v20, 16, v40
	s_waitcnt lgkmcnt(0)
	v_and_b32_e32 v21, 0xffff0000, v40
	v_lshlrev_b32_e32 v22, 16, v41
	v_and_b32_e32 v23, 0xffff0000, v41
	v_lshlrev_b32_e32 v26, 16, v43
	v_and_b32_e32 v27, 0xffff0000, v43
	v_pk_fma_f32 v[18:19], v[18:19], 0.5, v[22:23] op_sel_hi:[1,0,1]
	v_pk_fma_f32 v[16:17], v[16:17], 0.5, v[20:21] op_sel_hi:[1,0,1]
	v_lshlrev_b32_e32 v24, 16, v42
	v_and_b32_e32 v25, 0xffff0000, v42
	v_pk_fma_f32 v[22:23], v[14:15], 0.5, v[26:27] op_sel_hi:[1,0,1]
	v_mul_f32_e32 v14, v16, v16
	v_mul_f32_e32 v15, v18, v18
	v_pk_fma_f32 v[20:21], v[12:13], 0.5, v[24:25] op_sel_hi:[1,0,1]
	v_fmac_f32_e32 v14, v17, v17
	v_fmac_f32_e32 v15, v19, v19
	v_cvt_pk_bf16_f32 v12, v16, v17
	v_add_f32_e32 v14, v15, v14
	v_mul_f32_e32 v15, v20, v20
	v_mul_f32_e32 v16, v23, v23
	v_fmac_f32_e32 v15, v21, v21
	v_fmac_f32_e32 v16, v22, v22
	v_add_f32_e32 v15, v16, v15
	v_add_f32_e32 v26, v15, v14
	v_lshlrev_b32_e32 v14, 16, v36
	v_and_b32_e32 v15, 0xffff0000, v36
	v_lshlrev_b32_e32 v16, 16, v37
	v_and_b32_e32 v17, 0xffff0000, v37
	v_cvt_pk_bf16_f32 v13, v18, v19
	v_lshlrev_b32_e32 v18, 16, v38
	v_and_b32_e32 v19, 0xffff0000, v38
	v_pk_fma_f32 v[10:11], v[10:11], 0.5, v[16:17] op_sel_hi:[1,0,1]
	v_pk_fma_f32 v[8:9], v[8:9], 0.5, v[14:15] op_sel_hi:[1,0,1]
	v_lshlrev_b32_e32 v24, 16, v39
	v_and_b32_e32 v25, 0xffff0000, v39
	v_pk_fma_f32 v[16:17], v[4:5], 0.5, v[18:19] op_sel_hi:[1,0,1]
	v_mul_f32_e32 v4, v8, v8
	v_mul_f32_e32 v5, v10, v10
	v_pk_fma_f32 v[18:19], v[6:7], 0.5, v[24:25] op_sel_hi:[1,0,1]
	v_fmac_f32_e32 v4, v9, v9
	v_fmac_f32_e32 v5, v11, v11
	v_add_f32_e32 v4, v5, v4
	v_mul_f32_e32 v5, v16, v16
	v_mul_f32_e32 v6, v19, v19
	v_fmac_f32_e32 v5, v17, v17
	v_fmac_f32_e32 v6, v18, v18
	v_add_f32_e32 v5, v6, v5
	v_add_f32_e32 v4, v5, v4
	v_add_f32_e32 v4, v26, v4
	v_mov_b32_e32 v5, v4
	s_nop 1
	v_permlane16_swap_b32_e32 v5, v4
	v_cvt_pk_bf16_f32 v14, v20, v21
	v_cvt_pk_bf16_f32 v15, v22, v23
	global_store_dwordx4 v[46:47], v[12:15], off
	v_cvt_pk_bf16_f32 v6, v8, v9
	s_waitcnt lgkmcnt(0)
	v_add_f32_e32 v4, v4, v5
	v_mov_b32_e32 v5, v4
	s_nop 1
	v_permlane32_swap_b32_e32 v5, v4
	v_cvt_pk_bf16_f32 v7, v10, v11
	v_cvt_pk_bf16_f32 v8, v16, v17
	v_cvt_pk_bf16_f32 v9, v18, v19
	global_store_dwordx4 v[46:47], v[6:9], off offset:256
	s_and_saveexec_b64 s[14:15], s[2:3]
	s_cbranch_execz .LBB0_186
	s_waitcnt lgkmcnt(0)
	v_add_f32_e32 v4, v4, v5
	v_fma_f32 v4, v4, s60, 0.5
	v_cvt_u32_f32_e32 v4, v4
	v_lshl_add_u64 v[6:7], v[44:45], 2, s[8:9]
	global_atomic_add v[6:7], v4, off

; __device__ __forceinline__ unsigned cvt_pk_bf16(float lo, float hi) { unsigned r; asm volatile("v_cvt_pk_bf16_f32 %0, %1, %2" : "=v"(r) : "v"(lo), "v"(hi)); return r; }
;     __device__ __forceinline__ void operator()(const f32x4 (&acc)[2][2][4][2], const Unit& u, int wr, int wc, int fr, int fq, const float (&)[8]) const {
;         const int row0 = u.pm * BM + wr * 64 + fr, col0 = u.pn * BM + wc * 32 + 8 * fq;
;         u32x4 xc[2], xn[2];
;         { const size_t off = (size_t)row0 * 2048 + col0;
; #pragma unroll
;           for (int bj = 0; bj < 2; ++bj) xc[bj] = *(const u32x4*)(xb + off + bj * HALF); }
; #pragma unroll
;         for (int g = 0; g < 8; ++g) { const int ai = g >> 2, m = g & 3, row = row0 + ai * HALF + m * 16; const size_t off = (size_t)row * 2048 + col0; float ss = 0.f;
;             if (g + 1 < 8) { const size_t offn = (size_t)(row0 + ((g + 1) >> 2) * HALF + ((g + 1) & 3) * 16) * 2048 + col0;
; #pragma unroll
;                 for (int bj = 0; bj < 2; ++bj) xn[bj] = *(const u32x4*)(xb + offn + bj * HALF); }
; #pragma unroll
;             for (int bj = 0; bj < 2; ++bj) { const size_t o = off + bj * HALF; const u32x4 xw = xc[bj];
;                 const f32x4 x0 = (f32x4){__uint_as_float(xw.x << 16), __uint_as_float(xw.x & 0xffff0000u), __uint_as_float(xw.y << 16), __uint_as_float(xw.y & 0xffff0000u)};
;                 const f32x4 x1 = (f32x4){__uint_as_float(xw.z << 16), __uint_as_float(xw.z & 0xffff0000u), __uint_as_float(xw.w << 16), __uint_as_float(xw.w & 0xffff0000u)};
;                 const f32x4 v0 = x0 + acc[ai][bj][m][0] * alpha, v1 = x1 + acc[ai][bj][m][1] * alpha;
;                 if (xf) { *(f32x4*)(xf + o) = v0; *(f32x4*)(xf + o + 4) = v1; }
;                 else { u32x4 w; w.x = cvt_pk_bf16(v0[0], v0[1]); w.y = cvt_pk_bf16(v0[2], v0[3]); w.z = cvt_pk_bf16(v1[0], v1[1]); w.w = cvt_pk_bf16(v1[2], v1[3]); *(u32x4*)(xb + o) = w; }
;                 ss += ((v0[0] * v0[0] + v0[1] * v0[1]) + (v0[2] * v0[2] + v0[3] * v0[3])) + ((v1[0] * v1[0] + v1[1] * v1[1]) + (v1[2] * v1[2] + v1[3] * v1[3])); }
;             ss += __shfl_xor(ss, 16); ss += __shfl_xor(ss, 32);
;             if (fq == 0) (void)__hip_atomic_fetch_add((unsigned*)(ssq_out + row), (unsigned)(ss * SSQ_SCALE + 0.5f), __ATOMIC_RELAXED, __HIP_MEMORY_SCOPE_AGENT);
.LBB0_486:
	v_lshl_add_u32 v160, s18, 8, v184
	v_lshl_or_b32 v158, s20, 8, v186
	v_ashrrev_i32_e32 v161, 31, v160
	v_ashrrev_i32_e32 v159, 31, v158
	v_lshlrev_b64 v[132:133], 12, v[160:161]
	v_lshl_add_u64 v[132:133], s[46:47], 0, v[132:133]
	v_lshlrev_b64 v[134:135], 1, v[158:159]
	v_lshl_add_u64 v[166:167], v[132:133], 0, v[134:135]
	global_load_dwordx4 v[188:191], v[166:167], off
	global_load_dwordx4 v[192:195], v[166:167], off offset:256
	v_or_b32_e32 v162, 16, v160
	v_ashrrev_i32_e32 v163, 31, v162
	v_lshlrev_b64 v[132:133], 12, v[162:163]
	v_lshl_add_u64 v[132:133], s[46:47], 0, v[132:133]
	v_lshl_add_u64 v[164:165], v[132:133], 0, v[134:135]
	global_load_dwordx4 v[136:139], v[164:165], off
	global_load_dwordx4 v[132:135], v[164:165], off offset:256
	s_mov_b64 s[18:19], 0x20000
	v_lshl_add_u64 v[248:249], v[166:167], 0, s[18:19]
	global_load_dwordx4 v[200:203], v[248:249], off
	global_load_dwordx4 v[204:207], v[248:249], off offset:256
	s_mov_b64 s[18:19], 0x30000
	v_lshl_add_u64 v[248:249], v[166:167], 0, s[18:19]
	global_load_dwordx4 v[208:211], v[248:249], off
	global_load_dwordx4 v[212:215], v[248:249], off offset:256
	s_mov_b64 s[18:19], 0x80000
	v_lshl_add_u64 v[248:249], v[166:167], 0, s[18:19]
	global_load_dwordx4 v[216:219], v[248:249], off
	global_load_dwordx4 v[220:223], v[248:249], off offset:256
	s_mov_b64 s[18:19], 0x90000
	v_lshl_add_u64 v[248:249], v[166:167], 0, s[18:19]
	global_load_dwordx4 v[224:227], v[248:249], off
	global_load_dwordx4 v[228:231], v[248:249], off offset:256
	s_mov_b64 s[18:19], 0xa0000
	v_lshl_add_u64 v[248:249], v[166:167], 0, s[18:19]
	global_load_dwordx4 v[232:235], v[248:249], off
	global_load_dwordx4 v[236:239], v[248:249], off offset:256
	s_mov_b64 s[18:19], 0xb0000
	v_lshl_add_u64 v[248:249], v[166:167], 0, s[18:19]
	global_load_dwordx4 v[240:243], v[248:249], off
	global_load_dwordx4 v[244:247], v[248:249], off offset:256
	s_waitcnt vmcnt(14)
	v_lshlrev_b32_e32 v196, 16, v188
	v_and_b32_e32 v197, 0xffff0000, v188
	v_lshlrev_b32_e32 v188, 16, v189
	v_and_b32_e32 v189, 0xffff0000, v189
	v_lshlrev_b32_e32 v198, 16, v190
	v_and_b32_e32 v199, 0xffff0000, v190
	v_lshlrev_b32_e32 v190, 16, v191
	v_and_b32_e32 v191, 0xffff0000, v191
	v_pk_add_f32 v[130:131], v[130:131], v[188:189]
	v_pk_add_f32 v[128:129], v[128:129], v[196:197]
	v_pk_add_f32 v[188:189], v[124:125], v[198:199]
	v_cvt_pk_bf16_f32 v124, v128, v129
	v_cvt_pk_bf16_f32 v125, v130, v131
	v_pk_add_f32 v[190:191], v[126:127], v[190:191]
	v_cvt_pk_bf16_f32 v126, v188, v189
	s_nop 0
	v_cvt_pk_bf16_f32 v127, v190, v191
	global_store_dwordx4 v[166:167], v[124:127], off
	s_nop 1
	v_mul_f32_e32 v124, v128, v128
	v_mul_f32_e32 v125, v130, v130
	v_fmac_f32_e32 v124, v129, v129
	v_fmac_f32_e32 v125, v131, v131
	v_add_f32_e32 v124, v125, v124
	v_mul_f32_e32 v125, v188, v188
	v_mul_f32_e32 v126, v191, v191
	v_fmac_f32_e32 v125, v189, v189
	v_fmac_f32_e32 v126, v190, v190
	v_add_f32_e32 v125, v126, v125
	v_add_f32_e32 v188, v125, v124
	v_lshlrev_b32_e32 v124, 16, v192
	v_and_b32_e32 v125, 0xffff0000, v192
	v_lshlrev_b32_e32 v126, 16, v193
	v_and_b32_e32 v127, 0xffff0000, v193
	v_lshlrev_b32_e32 v128, 16, v194
	v_and_b32_e32 v129, 0xffff0000, v194
	v_lshlrev_b32_e32 v130, 16, v195
	v_and_b32_e32 v131, 0xffff0000, v195
	v_pk_add_f32 v[122:123], v[122:123], v[126:127]
	v_pk_add_f32 v[120:121], v[120:121], v[124:125]
	v_pk_add_f32 v[124:125], v[116:117], v[128:129]
	v_cvt_pk_bf16_f32 v116, v120, v121
	v_cvt_pk_bf16_f32 v117, v122, v123
	v_pk_add_f32 v[126:127], v[118:119], v[130:131]
	v_cvt_pk_bf16_f32 v118, v124, v125
	s_nop 0
	v_cvt_pk_bf16_f32 v119, v126, v127
	global_store_dwordx4 v[166:167], v[116:119], off offset:256
	s_nop 1
	v_mul_f32_e32 v116, v120, v120
	v_mul_f32_e32 v117, v122, v122
	v_fmac_f32_e32 v116, v121, v121
	v_fmac_f32_e32 v117, v123, v123
	v_add_f32_e32 v116, v117, v116
	v_mul_f32_e32 v117, v124, v124
	v_mul_f32_e32 v118, v127, v127
	v_fmac_f32_e32 v117, v125, v125
	v_fmac_f32_e32 v118, v126, v126
	v_add_f32_e32 v117, v118, v117
	v_and_b32_e32 v118, 64, v169
	v_add_f32_e32 v116, v117, v116
	v_xor_b32_e32 v117, 16, v169
	v_add_u32_e32 v118, 64, v118
	v_cmp_lt_i32_e32 vcc, v117, v118
	v_add_f32_e32 v116, v188, v116
	s_nop 0
	v_cndmask_b32_e32 v117, v169, v117, vcc
	v_lshlrev_b32_e32 v128, 2, v117
	v_mov_b32_e32 v117, v116
	s_nop 1
	v_permlane16_swap_b32_e32 v117, v116
	s_waitcnt lgkmcnt(0)
	v_add_f32_e32 v116, v116, v117
	v_xor_b32_e32 v117, 32, v169
	v_cmp_lt_i32_e32 vcc, v117, v118
	s_nop 1
	v_cndmask_b32_e32 v117, v169, v117, vcc
	v_lshlrev_b32_e32 v129, 2, v117
	v_mov_b32_e32 v117, v116
	s_nop 1
	v_permlane32_swap_b32_e32 v117, v116
	s_and_saveexec_b64 s[18:19], s[2:3]
	s_cbranch_execz .LBB0_488
	s_waitcnt lgkmcnt(0)
	v_add_f32_e32 v116, v116, v117
	v_fma_f32 v116, v116, s60, 0.5
	v_cvt_u32_f32_e32 v118, v116
	v_lshl_add_u64 v[116:117], v[160:161], 2, s[0:1]
	global_atomic_add v[116:117], v118, off
; __device__ __forceinline__ unsigned cvt_pk_bf16(float lo, float hi) { unsigned r; asm volatile("v_cvt_pk_bf16_f32 %0, %1, %2" : "=v"(r) : "v"(lo), "v"(hi)); return r; }
;     __device__ __forceinline__ void operator()(const f32x4 (&acc)[2][2][4][2], const Unit& u, int wr, int wc, int fr, int fq, const float (&)[8]) const {
;     ...
;         for (int g = 0; g < 8; ++g) { const int ai = g >> 2, m = g & 3, row = row0 + ai * HALF + m * 16; const size_t off = (size_t)row * 2048 + col0; float ss = 0.f;
;             if (g + 1 < 8) { const size_t offn = (size_t)(row0 + ((g + 1) >> 2) * HALF + ((g + 1) & 3) * 16) * 2048 + col0;
; #pragma unroll
;                 for (int bj = 0; bj < 2; ++bj) xn[bj] = *(const u32x4*)(xb + offn + bj * HALF); }
; #pragma unroll
;             for (int bj = 0; bj < 2; ++bj) { const size_t o = off + bj * HALF; const u32x4 xw = xc[bj];
;                 const f32x4 x0 = (f32x4){__uint_as_float(xw.x << 16), __uint_as_float(xw.x & 0xffff0000u), __uint_as_float(xw.y << 16), __uint_as_float(xw.y & 0xffff0000u)};
;                 const f32x4 x1 = (f32x4){__uint_as_float(xw.z << 16), __uint_as_float(xw.z & 0xffff0000u), __uint_as_float(xw.w << 16), __uint_as_float(xw.w & 0xffff0000u)};
;                 const f32x4 v0 = x0 + acc[ai][bj][m][0] * alpha, v1 = x1 + acc[ai][bj][m][1] * alpha;
;                 if (xf) { *(f32x4*)(xf + o) = v0; *(f32x4*)(xf + o + 4) = v1; }
;                 else { u32x4 w; w.x = cvt_pk_bf16(v0[0], v0[1]); w.y = cvt_pk_bf16(v0[2], v0[3]); w.z = cvt_pk_bf16(v1[0], v1[1]); w.w = cvt_pk_bf16(v1[2], v1[3]); *(u32x4*)(xb + o) = w; }
;                 ss += ((v0[0] * v0[0] + v0[1] * v0[1]) + (v0[2] * v0[2] + v0[3] * v0[3])) + ((v1[0] * v1[0] + v1[1] * v1[1]) + (v1[2] * v1[2] + v1[3] * v1[3])); }
;             ss += __shfl_xor(ss, 16); ss += __shfl_xor(ss, 32);
;             if (fq == 0) (void)__hip_atomic_fetch_add((unsigned*)(ssq_out + row), (unsigned)(ss * SSQ_SCALE + 0.5f), __ATOMIC_RELAXED, __HIP_MEMORY_SCOPE_AGENT);
; #pragma unroll
;             for (int bj = 0; bj < 2; ++bj) xc[bj] = xn[bj]; }
.LBB0_488:
	s_or_b64 exec, exec, s[18:19]
	v_or_b32_e32 v124, 32, v160
	v_ashrrev_i32_e32 v125, 31, v124
	s_waitcnt lgkmcnt(0)
	v_lshlrev_b64 v[116:117], 12, v[124:125]
	v_lshl_add_u64 v[116:117], s[46:47], 0, v[116:117]
	v_lshl_add_u64 v[126:127], v[158:159], 1, v[116:117]
	s_waitcnt vmcnt(12)
	v_mov_b32_e32 v120, v200
	v_mov_b32_e32 v121, v201
	v_mov_b32_e32 v122, v202
	v_mov_b32_e32 v123, v203
	v_mov_b32_e32 v116, v204
	v_mov_b32_e32 v117, v205
	v_mov_b32_e32 v118, v206
	v_mov_b32_e32 v119, v207
	v_lshlrev_b32_e32 v130, 16, v136
	v_and_b32_e32 v131, 0xffff0000, v136
	v_lshlrev_b32_e32 v136, 16, v137
	v_and_b32_e32 v137, 0xffff0000, v137
	v_lshlrev_b32_e32 v166, 16, v138
	v_and_b32_e32 v167, 0xffff0000, v138
	v_lshlrev_b32_e32 v138, 16, v139
	v_and_b32_e32 v139, 0xffff0000, v139
	v_pk_add_f32 v[114:115], v[114:115], v[136:137]
	v_pk_add_f32 v[112:113], v[112:113], v[130:131]
	v_pk_add_f32 v[136:137], v[110:111], v[138:139]
	v_mul_f32_e32 v110, v112, v112
	v_mul_f32_e32 v111, v114, v114
	v_pk_add_f32 v[130:131], v[108:109], v[166:167]
	v_fmac_f32_e32 v110, v113, v113
	v_fmac_f32_e32 v111, v115, v115
	v_cvt_pk_bf16_f32 v108, v112, v113
	v_add_f32_e32 v110, v111, v110
	v_mul_f32_e32 v111, v130, v130
	v_mul_f32_e32 v112, v137, v137
	v_fmac_f32_e32 v111, v131, v131
	v_fmac_f32_e32 v112, v136, v136
	v_add_f32_e32 v111, v112, v111
	v_add_f32_e32 v138, v111, v110
	v_lshlrev_b32_e32 v110, 16, v132
	v_and_b32_e32 v111, 0xffff0000, v132
	v_lshlrev_b32_e32 v112, 16, v133
	v_and_b32_e32 v113, 0xffff0000, v133
	v_cvt_pk_bf16_f32 v109, v114, v115
	v_lshlrev_b32_e32 v114, 16, v134
	v_and_b32_e32 v115, 0xffff0000, v134
	v_pk_add_f32 v[106:107], v[106:107], v[112:113]
	v_pk_add_f32 v[104:105], v[104:105], v[110:111]
	v_lshlrev_b32_e32 v132, 16, v135
	v_and_b32_e32 v133, 0xffff0000, v135
	v_pk_add_f32 v[112:113], v[100:101], v[114:115]
	v_mul_f32_e32 v100, v104, v104
	v_mul_f32_e32 v101, v106, v106
	v_pk_add_f32 v[114:115], v[102:103], v[132:133]
	v_fmac_f32_e32 v100, v105, v105
	v_fmac_f32_e32 v101, v107, v107
	v_add_f32_e32 v100, v101, v100
	v_mul_f32_e32 v101, v112, v112
	v_mul_f32_e32 v102, v115, v115
	v_fmac_f32_e32 v101, v113, v113
	v_fmac_f32_e32 v102, v114, v114
	v_add_f32_e32 v101, v102, v101
	v_add_f32_e32 v100, v101, v100
	v_add_f32_e32 v100, v138, v100
	v_mov_b32_e32 v101, v100
	s_nop 1
	v_permlane16_swap_b32_e32 v101, v100
	v_cvt_pk_bf16_f32 v110, v130, v131
	v_cvt_pk_bf16_f32 v111, v136, v137
	global_store_dwordx4 v[164:165], v[108:111], off
	v_cvt_pk_bf16_f32 v102, v104, v105
	s_waitcnt lgkmcnt(0)
	v_add_f32_e32 v100, v100, v101
	v_mov_b32_e32 v101, v100
	s_nop 1
	v_permlane32_swap_b32_e32 v101, v100
	v_cvt_pk_bf16_f32 v103, v106, v107
	v_cvt_pk_bf16_f32 v104, v112, v113
	v_cvt_pk_bf16_f32 v105, v114, v115
	global_store_dwordx4 v[164:165], v[102:105], off offset:256
	s_and_saveexec_b64 s[18:19], s[2:3]
	s_cbranch_execz .LBB0_490
	s_waitcnt lgkmcnt(0)
	v_add_f32_e32 v100, v100, v101
	v_fma_f32 v100, v100, s60, 0.5
	v_cvt_u32_f32_e32 v102, v100
	v_lshl_add_u64 v[100:101], v[162:163], 2, s[0:1]
	global_atomic_add v[100:101], v102, off
.LBB0_490:
	s_or_b64 exec, exec, s[18:19]
	v_or_b32_e32 v108, 48, v160
	v_ashrrev_i32_e32 v109, 31, v108
	s_waitcnt lgkmcnt(0)
	v_lshlrev_b64 v[100:101], 12, v[108:109]
	v_lshl_add_u64 v[100:101], s[46:47], 0, v[100:101]
	v_lshl_add_u64 v[110:111], v[158:159], 1, v[100:101]
	s_waitcnt vmcnt(12)
	v_mov_b32_e32 v104, v208
	v_mov_b32_e32 v105, v209
	v_mov_b32_e32 v106, v210
	v_mov_b32_e32 v107, v211
	v_mov_b32_e32 v100, v212
	v_mov_b32_e32 v101, v213
	v_mov_b32_e32 v102, v214
	v_mov_b32_e32 v103, v215
	v_lshlrev_b32_e32 v112, 16, v120
	v_and_b32_e32 v113, 0xffff0000, v120
	v_lshlrev_b32_e32 v114, 16, v121
	v_and_b32_e32 v115, 0xffff0000, v121
	v_lshlrev_b32_e32 v120, 16, v122
	v_and_b32_e32 v121, 0xffff0000, v122
	v_lshlrev_b32_e32 v122, 16, v123
	v_and_b32_e32 v123, 0xffff0000, v123
	v_pk_add_f32 v[98:99], v[98:99], v[114:115]
	v_pk_add_f32 v[96:97], v[96:97], v[112:113]
	v_pk_add_f32 v[114:115], v[94:95], v[122:123]
	v_mul_f32_e32 v94, v96, v96
	v_mul_f32_e32 v95, v98, v98
	v_pk_add_f32 v[112:113], v[92:93], v[120:121]
	v_fmac_f32_e32 v94, v97, v97
	v_fmac_f32_e32 v95, v99, v99
	v_cvt_pk_bf16_f32 v92, v96, v97
	v_add_f32_e32 v94, v95, v94
	v_mul_f32_e32 v95, v112, v112
	v_mul_f32_e32 v96, v115, v115
	v_fmac_f32_e32 v95, v113, v113
	v_fmac_f32_e32 v96, v114, v114
	v_add_f32_e32 v95, v96, v95
	v_add_f32_e32 v120, v95, v94
	v_lshlrev_b32_e32 v94, 16, v116
	v_and_b32_e32 v95, 0xffff0000, v116
	v_lshlrev_b32_e32 v96, 16, v117
	v_and_b32_e32 v97, 0xffff0000, v117
	v_cvt_pk_bf16_f32 v93, v98, v99
	v_lshlrev_b32_e32 v98, 16, v118
	v_and_b32_e32 v99, 0xffff0000, v118
	v_pk_add_f32 v[90:91], v[90:91], v[96:97]
	v_pk_add_f32 v[88:89], v[88:89], v[94:95]
	v_lshlrev_b32_e32 v116, 16, v119
	v_and_b32_e32 v117, 0xffff0000, v119
	v_pk_add_f32 v[96:97], v[84:85], v[98:99]
	v_mul_f32_e32 v84, v88, v88
	v_mul_f32_e32 v85, v90, v90
	v_pk_add_f32 v[98:99], v[86:87], v[116:117]
	v_fmac_f32_e32 v84, v89, v89
	v_fmac_f32_e32 v85, v91, v91
	v_add_f32_e32 v84, v85, v84
	v_mul_f32_e32 v85, v96, v96
	v_mul_f32_e32 v86, v99, v99
	v_fmac_f32_e32 v85, v97, v97
	v_fmac_f32_e32 v86, v98, v98
	v_add_f32_e32 v85, v86, v85
	v_add_f32_e32 v84, v85, v84
	v_add_f32_e32 v84, v120, v84
	v_mov_b32_e32 v85, v84
	s_nop 1
	v_permlane16_swap_b32_e32 v85, v84
	v_cvt_pk_bf16_f32 v94, v112, v113
	v_cvt_pk_bf16_f32 v95, v114, v115
	global_store_dwordx4 v[126:127], v[92:95], off
	v_cvt_pk_bf16_f32 v86, v88, v89
	s_waitcnt lgkmcnt(0)
	v_add_f32_e32 v84, v84, v85
	v_mov_b32_e32 v85, v84
	s_nop 1
	v_permlane32_swap_b32_e32 v85, v84
	v_cvt_pk_bf16_f32 v87, v90, v91
	v_cvt_pk_bf16_f32 v88, v96, v97
	v_cvt_pk_bf16_f32 v89, v98, v99
	global_store_dwordx4 v[126:127], v[86:89], off offset:256
	s_and_saveexec_b64 s[18:19], s[2:3]
	s_cbranch_execz .LBB0_492
	s_waitcnt lgkmcnt(0)
	v_add_f32_e32 v84, v84, v85
	v_fma_f32 v84, v84, s60, 0.5
	v_cvt_u32_f32_e32 v86, v84
	v_lshl_add_u64 v[84:85], v[124:125], 2, s[0:1]
	global_atomic_add v[84:85], v86, off
; __device__ __forceinline__ unsigned cvt_pk_bf16(float lo, float hi) { unsigned r; asm volatile("v_cvt_pk_bf16_f32 %0, %1, %2" : "=v"(r) : "v"(lo), "v"(hi)); return r; }
;     __device__ __forceinline__ void operator()(const f32x4 (&acc)[2][2][4][2], const Unit& u, int wr, int wc, int fr, int fq, const float (&)[8]) const {
;     ...
;         for (int g = 0; g < 8; ++g) { const int ai = g >> 2, m = g & 3, row = row0 + ai * HALF + m * 16; const size_t off = (size_t)row * 2048 + col0; float ss = 0.f;
;             if (g + 1 < 8) { const size_t offn = (size_t)(row0 + ((g + 1) >> 2) * HALF + ((g + 1) & 3) * 16) * 2048 + col0;
; #pragma unroll
;                 for (int bj = 0; bj < 2; ++bj) xn[bj] = *(const u32x4*)(xb + offn + bj * HALF); }
; #pragma unroll
;             for (int bj = 0; bj < 2; ++bj) { const size_t o = off + bj * HALF; const u32x4 xw = xc[bj];
;                 const f32x4 x0 = (f32x4){__uint_as_float(xw.x << 16), __uint_as_float(xw.x & 0xffff0000u), __uint_as_float(xw.y << 16), __uint_as_float(xw.y & 0xffff0000u)};
;                 const f32x4 x1 = (f32x4){__uint_as_float(xw.z << 16), __uint_as_float(xw.z & 0xffff0000u), __uint_as_float(xw.w << 16), __uint_as_float(xw.w & 0xffff0000u)};
;                 const f32x4 v0 = x0 + acc[ai][bj][m][0] * alpha, v1 = x1 + acc[ai][bj][m][1] * alpha;
;                 if (xf) { *(f32x4*)(xf + o) = v0; *(f32x4*)(xf + o + 4) = v1; }
;                 else { u32x4 w; w.x = cvt_pk_bf16(v0[0], v0[1]); w.y = cvt_pk_bf16(v0[2], v0[3]); w.z = cvt_pk_bf16(v1[0], v1[1]); w.w = cvt_pk_bf16(v1[2], v1[3]); *(u32x4*)(xb + o) = w; }
;                 ss += ((v0[0] * v0[0] + v0[1] * v0[1]) + (v0[2] * v0[2] + v0[3] * v0[3])) + ((v1[0] * v1[0] + v1[1] * v1[1]) + (v1[2] * v1[2] + v1[3] * v1[3])); }
;             ss += __shfl_xor(ss, 16); ss += __shfl_xor(ss, 32);
;             if (fq == 0) (void)__hip_atomic_fetch_add((unsigned*)(ssq_out + row), (unsigned)(ss * SSQ_SCALE + 0.5f), __ATOMIC_RELAXED, __HIP_MEMORY_SCOPE_AGENT);
; #pragma unroll
;             for (int bj = 0; bj < 2; ++bj) xc[bj] = xn[bj]; }
.LBB0_492:
	s_or_b64 exec, exec, s[18:19]
	v_add_u32_e32 v92, 0x80, v160
	v_ashrrev_i32_e32 v93, 31, v92
	s_waitcnt lgkmcnt(0)
	v_lshlrev_b64 v[84:85], 12, v[92:93]
	v_lshl_add_u64 v[84:85], s[46:47], 0, v[84:85]
	v_lshl_add_u64 v[94:95], v[158:159], 1, v[84:85]
	s_waitcnt vmcnt(12)
	v_mov_b32_e32 v88, v216
	v_mov_b32_e32 v89, v217
	v_mov_b32_e32 v90, v218
	v_mov_b32_e32 v91, v219
	v_mov_b32_e32 v84, v220
	v_mov_b32_e32 v85, v221
	v_mov_b32_e32 v86, v222
	v_mov_b32_e32 v87, v223
	v_lshlrev_b32_e32 v96, 16, v104
	v_and_b32_e32 v97, 0xffff0000, v104
	v_lshlrev_b32_e32 v98, 16, v105
	v_and_b32_e32 v99, 0xffff0000, v105
	v_lshlrev_b32_e32 v104, 16, v106
	v_and_b32_e32 v105, 0xffff0000, v106
	v_lshlrev_b32_e32 v106, 16, v107
	v_and_b32_e32 v107, 0xffff0000, v107
	v_pk_add_f32 v[82:83], v[82:83], v[98:99]
	v_pk_add_f32 v[80:81], v[80:81], v[96:97]
	v_pk_add_f32 v[98:99], v[78:79], v[106:107]
	v_mul_f32_e32 v78, v80, v80
	v_mul_f32_e32 v79, v82, v82
	v_pk_add_f32 v[96:97], v[76:77], v[104:105]
	v_fmac_f32_e32 v78, v81, v81
	v_fmac_f32_e32 v79, v83, v83
	v_cvt_pk_bf16_f32 v76, v80, v81
	v_add_f32_e32 v78, v79, v78
	v_mul_f32_e32 v79, v96, v96
	v_mul_f32_e32 v80, v99, v99
	v_fmac_f32_e32 v79, v97, v97
	v_fmac_f32_e32 v80, v98, v98
	v_add_f32_e32 v79, v80, v79
	v_add_f32_e32 v104, v79, v78
	v_lshlrev_b32_e32 v78, 16, v100
	v_and_b32_e32 v79, 0xffff0000, v100
	v_lshlrev_b32_e32 v80, 16, v101
	v_and_b32_e32 v81, 0xffff0000, v101
	v_cvt_pk_bf16_f32 v77, v82, v83
	v_lshlrev_b32_e32 v82, 16, v102
	v_and_b32_e32 v83, 0xffff0000, v102
	v_pk_add_f32 v[74:75], v[74:75], v[80:81]
	v_pk_add_f32 v[72:73], v[72:73], v[78:79]
	v_lshlrev_b32_e32 v100, 16, v103
	v_and_b32_e32 v101, 0xffff0000, v103
	v_pk_add_f32 v[80:81], v[68:69], v[82:83]
	v_mul_f32_e32 v68, v72, v72
	v_mul_f32_e32 v69, v74, v74
	v_pk_add_f32 v[82:83], v[70:71], v[100:101]
	v_fmac_f32_e32 v68, v73, v73
	v_fmac_f32_e32 v69, v75, v75
	v_add_f32_e32 v68, v69, v68
	v_mul_f32_e32 v69, v80, v80
	v_mul_f32_e32 v70, v83, v83
	v_fmac_f32_e32 v69, v81, v81
	v_fmac_f32_e32 v70, v82, v82
	v_add_f32_e32 v69, v70, v69
	v_add_f32_e32 v68, v69, v68
	v_add_f32_e32 v68, v104, v68
	v_mov_b32_e32 v69, v68
	s_nop 1
	v_permlane16_swap_b32_e32 v69, v68
	v_cvt_pk_bf16_f32 v78, v96, v97
	v_cvt_pk_bf16_f32 v79, v98, v99
	global_store_dwordx4 v[110:111], v[76:79], off
	v_cvt_pk_bf16_f32 v70, v72, v73
	s_waitcnt lgkmcnt(0)
	v_add_f32_e32 v68, v68, v69
	v_mov_b32_e32 v69, v68
	s_nop 1
	v_permlane32_swap_b32_e32 v69, v68
	v_cvt_pk_bf16_f32 v71, v74, v75
	v_cvt_pk_bf16_f32 v72, v80, v81
	v_cvt_pk_bf16_f32 v73, v82, v83
	global_store_dwordx4 v[110:111], v[70:73], off offset:256
	s_and_saveexec_b64 s[18:19], s[2:3]
	s_cbranch_execz .LBB0_494
	s_waitcnt lgkmcnt(0)
	v_add_f32_e32 v68, v68, v69
	v_fma_f32 v68, v68, s60, 0.5
	v_cvt_u32_f32_e32 v70, v68
	v_lshl_add_u64 v[68:69], v[108:109], 2, s[0:1]
	global_atomic_add v[68:69], v70, off
.LBB0_494:
	s_or_b64 exec, exec, s[18:19]
	v_or_b32_e32 v76, 16, v92
	v_ashrrev_i32_e32 v77, 31, v76
	s_waitcnt lgkmcnt(0)
	v_lshlrev_b64 v[68:69], 12, v[76:77]
	v_lshl_add_u64 v[68:69], s[46:47], 0, v[68:69]
	v_lshl_add_u64 v[78:79], v[158:159], 1, v[68:69]
	s_waitcnt vmcnt(12)
	v_mov_b32_e32 v72, v224
	v_mov_b32_e32 v73, v225
	v_mov_b32_e32 v74, v226
	v_mov_b32_e32 v75, v227
	v_mov_b32_e32 v68, v228
	v_mov_b32_e32 v69, v229
	v_mov_b32_e32 v70, v230
	v_mov_b32_e32 v71, v231
	v_lshlrev_b32_e32 v80, 16, v88
	v_and_b32_e32 v81, 0xffff0000, v88
	v_lshlrev_b32_e32 v82, 16, v89
	v_and_b32_e32 v83, 0xffff0000, v89
	v_lshlrev_b32_e32 v88, 16, v90
	v_and_b32_e32 v89, 0xffff0000, v90
	v_lshlrev_b32_e32 v90, 16, v91
	v_and_b32_e32 v91, 0xffff0000, v91
	v_pk_add_f32 v[66:67], v[66:67], v[82:83]
	v_pk_add_f32 v[64:65], v[64:65], v[80:81]
	v_pk_add_f32 v[82:83], v[62:63], v[90:91]
	v_mul_f32_e32 v62, v64, v64
	v_mul_f32_e32 v63, v66, v66
	v_pk_add_f32 v[80:81], v[60:61], v[88:89]
	v_fmac_f32_e32 v62, v65, v65
	v_fmac_f32_e32 v63, v67, v67
	v_cvt_pk_bf16_f32 v60, v64, v65
	v_add_f32_e32 v62, v63, v62
	v_mul_f32_e32 v63, v80, v80
	v_mul_f32_e32 v64, v83, v83
	v_fmac_f32_e32 v63, v81, v81
	v_fmac_f32_e32 v64, v82, v82
	v_add_f32_e32 v63, v64, v63
	v_add_f32_e32 v88, v63, v62
	v_lshlrev_b32_e32 v62, 16, v84
	v_and_b32_e32 v63, 0xffff0000, v84
	v_lshlrev_b32_e32 v64, 16, v85
	v_and_b32_e32 v65, 0xffff0000, v85
	v_cvt_pk_bf16_f32 v61, v66, v67
	v_lshlrev_b32_e32 v66, 16, v86
	v_and_b32_e32 v67, 0xffff0000, v86
	v_pk_add_f32 v[58:59], v[58:59], v[64:65]
	v_pk_add_f32 v[56:57], v[56:57], v[62:63]
	v_lshlrev_b32_e32 v84, 16, v87
	v_and_b32_e32 v85, 0xffff0000, v87
	v_pk_add_f32 v[64:65], v[52:53], v[66:67]
	v_mul_f32_e32 v52, v56, v56
	v_mul_f32_e32 v53, v58, v58
	v_pk_add_f32 v[66:67], v[54:55], v[84:85]
	v_fmac_f32_e32 v52, v57, v57
	v_fmac_f32_e32 v53, v59, v59
	v_add_f32_e32 v52, v53, v52
	v_mul_f32_e32 v53, v64, v64
	v_mul_f32_e32 v54, v67, v67
	v_fmac_f32_e32 v53, v65, v65
	v_fmac_f32_e32 v54, v66, v66
	v_add_f32_e32 v53, v54, v53
	v_add_f32_e32 v52, v53, v52
	v_add_f32_e32 v52, v88, v52
	v_mov_b32_e32 v53, v52
	s_nop 1
	v_permlane16_swap_b32_e32 v53, v52
	v_cvt_pk_bf16_f32 v62, v80, v81
	v_cvt_pk_bf16_f32 v63, v82, v83
	global_store_dwordx4 v[94:95], v[60:63], off
	v_cvt_pk_bf16_f32 v54, v56, v57
	s_waitcnt lgkmcnt(0)
	v_add_f32_e32 v52, v52, v53
	v_mov_b32_e32 v53, v52
	s_nop 1
	v_permlane32_swap_b32_e32 v53, v52
	v_cvt_pk_bf16_f32 v55, v58, v59
	v_cvt_pk_bf16_f32 v56, v64, v65
	v_cvt_pk_bf16_f32 v57, v66, v67
	global_store_dwordx4 v[94:95], v[54:57], off offset:256
	s_and_saveexec_b64 s[18:19], s[2:3]
	s_cbranch_execz .LBB0_496
	s_waitcnt lgkmcnt(0)
	v_add_f32_e32 v52, v52, v53
	v_fma_f32 v52, v52, s60, 0.5
	v_cvt_u32_f32_e32 v54, v52
	v_lshl_add_u64 v[52:53], v[92:93], 2, s[0:1]
	global_atomic_add v[52:53], v54, off
; __device__ __forceinline__ unsigned cvt_pk_bf16(float lo, float hi) { unsigned r; asm volatile("v_cvt_pk_bf16_f32 %0, %1, %2" : "=v"(r) : "v"(lo), "v"(hi)); return r; }
;     __device__ __forceinline__ void operator()(const f32x4 (&acc)[2][2][4][2], const Unit& u, int wr, int wc, int fr, int fq, const float (&)[8]) const {
;     ...
;         for (int g = 0; g < 8; ++g) { const int ai = g >> 2, m = g & 3, row = row0 + ai * HALF + m * 16; const size_t off = (size_t)row * 2048 + col0; float ss = 0.f;
;             if (g + 1 < 8) { const size_t offn = (size_t)(row0 + ((g + 1) >> 2) * HALF + ((g + 1) & 3) * 16) * 2048 + col0;
; #pragma unroll
;                 for (int bj = 0; bj < 2; ++bj) xn[bj] = *(const u32x4*)(xb + offn + bj * HALF); }
; #pragma unroll
;             for (int bj = 0; bj < 2; ++bj) { const size_t o = off + bj * HALF; const u32x4 xw = xc[bj];
;                 const f32x4 x0 = (f32x4){__uint_as_float(xw.x << 16), __uint_as_float(xw.x & 0xffff0000u), __uint_as_float(xw.y << 16), __uint_as_float(xw.y & 0xffff0000u)};
;                 const f32x4 x1 = (f32x4){__uint_as_float(xw.z << 16), __uint_as_float(xw.z & 0xffff0000u), __uint_as_float(xw.w << 16), __uint_as_float(xw.w & 0xffff0000u)};
;                 const f32x4 v0 = x0 + acc[ai][bj][m][0] * alpha, v1 = x1 + acc[ai][bj][m][1] * alpha;
;                 if (xf) { *(f32x4*)(xf + o) = v0; *(f32x4*)(xf + o + 4) = v1; }
;                 else { u32x4 w; w.x = cvt_pk_bf16(v0[0], v0[1]); w.y = cvt_pk_bf16(v0[2], v0[3]); w.z = cvt_pk_bf16(v1[0], v1[1]); w.w = cvt_pk_bf16(v1[2], v1[3]); *(u32x4*)(xb + o) = w; }
;                 ss += ((v0[0] * v0[0] + v0[1] * v0[1]) + (v0[2] * v0[2] + v0[3] * v0[3])) + ((v1[0] * v1[0] + v1[1] * v1[1]) + (v1[2] * v1[2] + v1[3] * v1[3])); }
;             ss += __shfl_xor(ss, 16); ss += __shfl_xor(ss, 32);
;             if (fq == 0) (void)__hip_atomic_fetch_add((unsigned*)(ssq_out + row), (unsigned)(ss * SSQ_SCALE + 0.5f), __ATOMIC_RELAXED, __HIP_MEMORY_SCOPE_AGENT);
; #pragma unroll
;             for (int bj = 0; bj < 2; ++bj) xc[bj] = xn[bj]; }
.LBB0_496:
	s_or_b64 exec, exec, s[18:19]
	v_or_b32_e32 v60, 32, v92
	v_ashrrev_i32_e32 v61, 31, v60
	s_waitcnt lgkmcnt(0)
	v_lshlrev_b64 v[52:53], 12, v[60:61]
	v_lshl_add_u64 v[52:53], s[46:47], 0, v[52:53]
	v_lshl_add_u64 v[62:63], v[158:159], 1, v[52:53]
	s_waitcnt vmcnt(12)
	v_mov_b32_e32 v56, v232
	v_mov_b32_e32 v57, v233
	v_mov_b32_e32 v58, v234
	v_mov_b32_e32 v59, v235
	v_mov_b32_e32 v52, v236
	v_mov_b32_e32 v53, v237
	v_mov_b32_e32 v54, v238
	v_mov_b32_e32 v55, v239
	v_lshlrev_b32_e32 v64, 16, v72
	v_and_b32_e32 v65, 0xffff0000, v72
	v_lshlrev_b32_e32 v66, 16, v73
	v_and_b32_e32 v67, 0xffff0000, v73
	v_lshlrev_b32_e32 v72, 16, v74
	v_and_b32_e32 v73, 0xffff0000, v74
	v_lshlrev_b32_e32 v74, 16, v75
	v_and_b32_e32 v75, 0xffff0000, v75
	v_pk_add_f32 v[50:51], v[50:51], v[66:67]
	v_pk_add_f32 v[48:49], v[48:49], v[64:65]
	v_pk_add_f32 v[66:67], v[46:47], v[74:75]
	v_mul_f32_e32 v46, v48, v48
	v_mul_f32_e32 v47, v50, v50
	v_pk_add_f32 v[64:65], v[44:45], v[72:73]
	v_fmac_f32_e32 v46, v49, v49
	v_fmac_f32_e32 v47, v51, v51
	v_cvt_pk_bf16_f32 v44, v48, v49
	v_add_f32_e32 v46, v47, v46
	v_mul_f32_e32 v47, v64, v64
	v_mul_f32_e32 v48, v67, v67
	v_fmac_f32_e32 v47, v65, v65
	v_fmac_f32_e32 v48, v66, v66
	v_add_f32_e32 v47, v48, v47
	v_add_f32_e32 v72, v47, v46
	v_lshlrev_b32_e32 v46, 16, v68
	v_and_b32_e32 v47, 0xffff0000, v68
	v_lshlrev_b32_e32 v48, 16, v69
	v_and_b32_e32 v49, 0xffff0000, v69
	v_cvt_pk_bf16_f32 v45, v50, v51
	v_lshlrev_b32_e32 v50, 16, v70
	v_and_b32_e32 v51, 0xffff0000, v70
	v_pk_add_f32 v[42:43], v[42:43], v[48:49]
	v_pk_add_f32 v[40:41], v[40:41], v[46:47]
	v_lshlrev_b32_e32 v68, 16, v71
	v_and_b32_e32 v69, 0xffff0000, v71
	v_pk_add_f32 v[48:49], v[36:37], v[50:51]
	v_mul_f32_e32 v36, v40, v40
	v_mul_f32_e32 v37, v42, v42
	v_pk_add_f32 v[50:51], v[38:39], v[68:69]
	v_fmac_f32_e32 v36, v41, v41
	v_fmac_f32_e32 v37, v43, v43
	v_add_f32_e32 v36, v37, v36
	v_mul_f32_e32 v37, v48, v48
	v_mul_f32_e32 v38, v51, v51
	v_fmac_f32_e32 v37, v49, v49
	v_fmac_f32_e32 v38, v50, v50
	v_add_f32_e32 v37, v38, v37
	v_add_f32_e32 v36, v37, v36
	v_add_f32_e32 v36, v72, v36
	v_mov_b32_e32 v37, v36
	s_nop 1
	v_permlane16_swap_b32_e32 v37, v36
	v_cvt_pk_bf16_f32 v46, v64, v65
	v_cvt_pk_bf16_f32 v47, v66, v67
	global_store_dwordx4 v[78:79], v[44:47], off
	v_cvt_pk_bf16_f32 v38, v40, v41
	s_waitcnt lgkmcnt(0)
	v_add_f32_e32 v36, v36, v37
	v_mov_b32_e32 v37, v36
	s_nop 1
	v_permlane32_swap_b32_e32 v37, v36
	v_cvt_pk_bf16_f32 v39, v42, v43
	v_cvt_pk_bf16_f32 v40, v48, v49
	v_cvt_pk_bf16_f32 v41, v50, v51
	global_store_dwordx4 v[78:79], v[38:41], off offset:256
	s_and_saveexec_b64 s[18:19], s[2:3]
	s_cbranch_execz .LBB0_498
	s_waitcnt lgkmcnt(0)
	v_add_f32_e32 v36, v36, v37
	v_fma_f32 v36, v36, s60, 0.5
	v_cvt_u32_f32_e32 v38, v36
	v_lshl_add_u64 v[36:37], v[76:77], 2, s[0:1]
	global_atomic_add v[36:37], v38, off
; __device__ __forceinline__ unsigned cvt_pk_bf16(float lo, float hi) { unsigned r; asm volatile("v_cvt_pk_bf16_f32 %0, %1, %2" : "=v"(r) : "v"(lo), "v"(hi)); return r; }
;     __device__ __forceinline__ void operator()(const f32x4 (&acc)[2][2][4][2], const Unit& u, int wr, int wc, int fr, int fq, const float (&)[8]) const {
;     ...
;         for (int g = 0; g < 8; ++g) { const int ai = g >> 2, m = g & 3, row = row0 + ai * HALF + m * 16; const size_t off = (size_t)row * 2048 + col0; float ss = 0.f;
;             if (g + 1 < 8) { const size_t offn = (size_t)(row0 + ((g + 1) >> 2) * HALF + ((g + 1) & 3) * 16) * 2048 + col0;
; #pragma unroll
;                 for (int bj = 0; bj < 2; ++bj) xn[bj] = *(const u32x4*)(xb + offn + bj * HALF); }
; #pragma unroll
;             for (int bj = 0; bj < 2; ++bj) { const size_t o = off + bj * HALF; const u32x4 xw = xc[bj];
;                 const f32x4 x0 = (f32x4){__uint_as_float(xw.x << 16), __uint_as_float(xw.x & 0xffff0000u), __uint_as_float(xw.y << 16), __uint_as_float(xw.y & 0xffff0000u)};
;                 const f32x4 x1 = (f32x4){__uint_as_float(xw.z << 16), __uint_as_float(xw.z & 0xffff0000u), __uint_as_float(xw.w << 16), __uint_as_float(xw.w & 0xffff0000u)};
;                 const f32x4 v0 = x0 + acc[ai][bj][m][0] * alpha, v1 = x1 + acc[ai][bj][m][1] * alpha;
;                 if (xf) { *(f32x4*)(xf + o) = v0; *(f32x4*)(xf + o + 4) = v1; }
;                 else { u32x4 w; w.x = cvt_pk_bf16(v0[0], v0[1]); w.y = cvt_pk_bf16(v0[2], v0[3]); w.z = cvt_pk_bf16(v1[0], v1[1]); w.w = cvt_pk_bf16(v1[2], v1[3]); *(u32x4*)(xb + o) = w; }
;                 ss += ((v0[0] * v0[0] + v0[1] * v0[1]) + (v0[2] * v0[2] + v0[3] * v0[3])) + ((v1[0] * v1[0] + v1[1] * v1[1]) + (v1[2] * v1[2] + v1[3] * v1[3])); }
;             ss += __shfl_xor(ss, 16); ss += __shfl_xor(ss, 32);
;             if (fq == 0) (void)__hip_atomic_fetch_add((unsigned*)(ssq_out + row), (unsigned)(ss * SSQ_SCALE + 0.5f), __ATOMIC_RELAXED, __HIP_MEMORY_SCOPE_AGENT);
; #pragma unroll
;             for (int bj = 0; bj < 2; ++bj) xc[bj] = xn[bj]; }
.LBB0_498:
	s_or_b64 exec, exec, s[18:19]
	v_or_b32_e32 v44, 48, v92
	v_ashrrev_i32_e32 v45, 31, v44
	s_waitcnt lgkmcnt(0)
	v_lshlrev_b64 v[36:37], 12, v[44:45]
	v_lshl_add_u64 v[36:37], s[46:47], 0, v[36:37]
	v_lshl_add_u64 v[46:47], v[158:159], 1, v[36:37]
	s_waitcnt vmcnt(12)
	v_mov_b32_e32 v40, v240
	v_mov_b32_e32 v41, v241
	v_mov_b32_e32 v42, v242
	v_mov_b32_e32 v43, v243
	v_mov_b32_e32 v36, v244
	v_mov_b32_e32 v37, v245
	v_mov_b32_e32 v38, v246
	v_mov_b32_e32 v39, v247
	v_lshlrev_b32_e32 v48, 16, v56
	v_and_b32_e32 v49, 0xffff0000, v56
	v_lshlrev_b32_e32 v50, 16, v57
	v_and_b32_e32 v51, 0xffff0000, v57
	v_lshlrev_b32_e32 v56, 16, v58
	v_and_b32_e32 v57, 0xffff0000, v58
	v_lshlrev_b32_e32 v58, 16, v59
	v_and_b32_e32 v59, 0xffff0000, v59
	v_pk_add_f32 v[34:35], v[34:35], v[50:51]
	v_pk_add_f32 v[32:33], v[32:33], v[48:49]
	v_pk_add_f32 v[50:51], v[30:31], v[58:59]
	v_mul_f32_e32 v30, v32, v32
	v_mul_f32_e32 v31, v34, v34
	v_pk_add_f32 v[48:49], v[28:29], v[56:57]
	v_fmac_f32_e32 v30, v33, v33
	v_fmac_f32_e32 v31, v35, v35
	v_cvt_pk_bf16_f32 v28, v32, v33
	v_add_f32_e32 v30, v31, v30
	v_mul_f32_e32 v31, v48, v48
	v_mul_f32_e32 v32, v51, v51
	v_fmac_f32_e32 v31, v49, v49
	v_fmac_f32_e32 v32, v50, v50
	v_add_f32_e32 v31, v32, v31
	v_add_f32_e32 v56, v31, v30
	v_lshlrev_b32_e32 v30, 16, v52
	v_and_b32_e32 v31, 0xffff0000, v52
	v_lshlrev_b32_e32 v32, 16, v53
	v_and_b32_e32 v33, 0xffff0000, v53
	v_cvt_pk_bf16_f32 v29, v34, v35
	v_lshlrev_b32_e32 v34, 16, v54
	v_and_b32_e32 v35, 0xffff0000, v54
	v_pk_add_f32 v[26:27], v[26:27], v[32:33]
	v_pk_add_f32 v[24:25], v[24:25], v[30:31]
	v_lshlrev_b32_e32 v52, 16, v55
	v_and_b32_e32 v53, 0xffff0000, v55
	v_pk_add_f32 v[32:33], v[20:21], v[34:35]
	v_mul_f32_e32 v20, v24, v24
	v_mul_f32_e32 v21, v26, v26
	v_pk_add_f32 v[34:35], v[22:23], v[52:53]
	v_fmac_f32_e32 v20, v25, v25
	v_fmac_f32_e32 v21, v27, v27
	v_add_f32_e32 v20, v21, v20
	v_mul_f32_e32 v21, v32, v32
	v_mul_f32_e32 v22, v35, v35
	v_fmac_f32_e32 v21, v33, v33
	v_fmac_f32_e32 v22, v34, v34
	v_add_f32_e32 v21, v22, v21
	v_add_f32_e32 v20, v21, v20
	v_add_f32_e32 v20, v56, v20
	v_mov_b32_e32 v21, v20
	s_nop 1
	v_permlane16_swap_b32_e32 v21, v20
	v_cvt_pk_bf16_f32 v30, v48, v49
	v_cvt_pk_bf16_f32 v31, v50, v51
	global_store_dwordx4 v[62:63], v[28:31], off
	v_cvt_pk_bf16_f32 v22, v24, v25
	s_waitcnt lgkmcnt(0)
	v_add_f32_e32 v20, v20, v21
	v_mov_b32_e32 v21, v20
	s_nop 1
	v_permlane32_swap_b32_e32 v21, v20
	v_cvt_pk_bf16_f32 v23, v26, v27
	v_cvt_pk_bf16_f32 v24, v32, v33
	v_cvt_pk_bf16_f32 v25, v34, v35
	global_store_dwordx4 v[62:63], v[22:25], off offset:256
	s_and_saveexec_b64 s[18:19], s[2:3]
	s_cbranch_execz .LBB0_500
	s_waitcnt lgkmcnt(0)
	v_add_f32_e32 v20, v20, v21
	v_fma_f32 v20, v20, s60, 0.5
	v_cvt_u32_f32_e32 v22, v20
	v_lshl_add_u64 v[20:21], v[60:61], 2, s[0:1]
	global_atomic_add v[20:21], v22, off
.LBB0_500:
	s_or_b64 exec, exec, s[18:19]
	v_lshlrev_b32_e32 v20, 16, v40
	s_waitcnt lgkmcnt(0)
	v_and_b32_e32 v21, 0xffff0000, v40
	v_lshlrev_b32_e32 v22, 16, v41
	v_and_b32_e32 v23, 0xffff0000, v41
	v_lshlrev_b32_e32 v26, 16, v43
	v_and_b32_e32 v27, 0xffff0000, v43
	v_pk_add_f32 v[18:19], v[18:19], v[22:23]
	v_pk_add_f32 v[16:17], v[16:17], v[20:21]
	v_lshlrev_b32_e32 v24, 16, v42
	v_and_b32_e32 v25, 0xffff0000, v42
	v_pk_add_f32 v[22:23], v[14:15], v[26:27]
	v_mul_f32_e32 v14, v16, v16
	v_mul_f32_e32 v15, v18, v18
	v_pk_add_f32 v[20:21], v[12:13], v[24:25]
	v_fmac_f32_e32 v14, v17, v17
	v_fmac_f32_e32 v15, v19, v19
	v_cvt_pk_bf16_f32 v12, v16, v17
	v_add_f32_e32 v14, v15, v14
	v_mul_f32_e32 v15, v20, v20
	v_mul_f32_e32 v16, v23, v23
	v_fmac_f32_e32 v15, v21, v21
	v_fmac_f32_e32 v16, v22, v22
	v_add_f32_e32 v15, v16, v15
	v_add_f32_e32 v26, v15, v14
	v_lshlrev_b32_e32 v14, 16, v36
	v_and_b32_e32 v15, 0xffff0000, v36
	v_lshlrev_b32_e32 v16, 16, v37
	v_and_b32_e32 v17, 0xffff0000, v37
	v_cvt_pk_bf16_f32 v13, v18, v19
	v_lshlrev_b32_e32 v18, 16, v38
	v_and_b32_e32 v19, 0xffff0000, v38
	v_pk_add_f32 v[10:11], v[10:11], v[16:17]
	v_pk_add_f32 v[8:9], v[8:9], v[14:15]
	v_lshlrev_b32_e32 v24, 16, v39
	v_and_b32_e32 v25, 0xffff0000, v39
	v_pk_add_f32 v[16:17], v[4:5], v[18:19]
	v_mul_f32_e32 v4, v8, v8
	v_mul_f32_e32 v5, v10, v10
	v_pk_add_f32 v[18:19], v[6:7], v[24:25]
	v_fmac_f32_e32 v4, v9, v9
	v_fmac_f32_e32 v5, v11, v11
	v_add_f32_e32 v4, v5, v4
	v_mul_f32_e32 v5, v16, v16
	v_mul_f32_e32 v6, v19, v19
	v_fmac_f32_e32 v5, v17, v17
	v_fmac_f32_e32 v6, v18, v18
	v_add_f32_e32 v5, v6, v5
	v_add_f32_e32 v4, v5, v4
	v_add_f32_e32 v4, v26, v4
	v_mov_b32_e32 v5, v4
	s_nop 1
	v_permlane16_swap_b32_e32 v5, v4
	v_cvt_pk_bf16_f32 v14, v20, v21
	v_cvt_pk_bf16_f32 v15, v22, v23
	global_store_dwordx4 v[46:47], v[12:15], off
	v_cvt_pk_bf16_f32 v6, v8, v9
	s_waitcnt lgkmcnt(0)
	v_add_f32_e32 v4, v4, v5
	v_mov_b32_e32 v5, v4
	s_nop 1
	v_permlane32_swap_b32_e32 v5, v4
	v_cvt_pk_bf16_f32 v7, v10, v11
	v_cvt_pk_bf16_f32 v8, v16, v17
	v_cvt_pk_bf16_f32 v9, v18, v19
	global_store_dwordx4 v[46:47], v[6:9], off offset:256
	s_and_saveexec_b64 s[18:19], s[2:3]
	s_cbranch_execz .LBB0_502
	s_waitcnt lgkmcnt(0)
	v_add_f32_e32 v4, v4, v5
	v_fma_f32 v4, v4, s60, 0.5
	v_cvt_u32_f32_e32 v4, v4
	v_lshl_add_u64 v[6:7], v[44:45], 2, s[0:1]
	global_atomic_add v[6:7], v4, off
